# baseline (speedup 1.0000x reference)
; #define STAGE_A(bufoff, gbase) STAGEX(bufoff, gbase, voffA)
; #define STAGE_B(bufoff, gbase) STAGEX(bufoff, gbase, voffB)
; #define LDA(dst, b, h) do { _Pragma("unroll") for (int m = 0; m < 4; ++m) _Pragma("unroll") for (int k = 0; k < 2; ++k) dst[m][k] = *(const __attribute__((address_space(3))) bf16x8*)(lds + SA(b, h) + aoff + m * 2048 + k * 1024); } while (0)
; #define LDB(dst, b, h) do { _Pragma("unroll") for (int n = 0; n < 2; ++n) _Pragma("unroll") for (int k = 0; k < 2; ++k) dst[n][k] = *(const __attribute__((address_space(3))) bf16x8*)(lds + SB_(b, h) + boff + n * 2048 + k * 1024); } while (0)
; #define MMA(ai, bj, At, Bt_) do { __builtin_amdgcn_s_setprio(1); _Pragma("unroll") for (int m = 0; m < 4; ++m) _Pragma("unroll") for (int n = 0; n < 2; ++n) _Pragma("unroll") for (int k = 0; k < 2; ++k) \
;       acc[ai][bj][m][n] = __builtin_amdgcn_mfma_f32_16x16x32_bf16(Bt_[n][k], At[m][k], acc[ai][bj][m][n], 0, 0, 0); \
;     __builtin_amdgcn_s_setprio(0); } while (0)
; #define WAIT_V(n) asm volatile("s_waitcnt vmcnt(" #n ")" ::: "memory")
; #define WAIT_L(n) asm volatile("s_waitcnt lgkmcnt(" #n ")" ::: "memory")
; #define BAR __builtin_amdgcn_s_barrier()
; #define SCHED __builtin_amdgcn_sched_barrier(0)
; template <int MODE>
; DEV void gemm_phase(const bf16_t* __restrict__ A, const bf16_t* __restrict__ Bt, int M, int N, int K, bf16_t* __restrict__ Out, int ldo,
;                     const float* __restrict__ rstd, const float* __restrict__ rope) {
;     ...
;     for (int t = 0; t < nt; t += 2) {
;       const bool last = (t == nt - 2);
;       const char* a1 = cA + (size_t)(t + 1) * 128;
;       const char* a2 = last ? nA : cA + (size_t)(t + 2) * 128; const char* b2 = last ? nB : cB + (size_t)(t + 2) * 128;
;       const char* a3 = a2 + 128; const char* b3 = b2 + 128;
;       LDB(B0, 0, 0); LDB(B1, 0, 1); SCHED; LDA(At, 0, 0); STAGE_A(SA(1, 1), a1 + hstep);
;       WAIT_V(8); WAIT_L(0); BAR; MMA(0, 0, At, B0); MMA(0, 1, At, B1); BAR; SCHED;
;       LDA(At, 0, 1); STAGE_B(SB_(0, 0), b2); STAGE_B(SB_(0, 1), b2 + hstep); STAGE_A(SA(0, 0), a2);
;       WAIT_V(8); WAIT_L(0); BAR; MMA(1, 0, At, B0); MMA(1, 1, At, B1); BAR; SCHED;
.LBB0_128:
	s_add_u32 s26, s44, s8
	s_addc_u32 s27, s45, s9
	s_add_u32 s26, s26, 0x12200100
	s_addc_u32 s27, s27, 0
	s_add_u32 s49, s46, s8
	s_addc_u32 s50, s47, s9
	s_add_i32 s51, 0, 0x10000
	s_cmpk_eq_i32 s8, 0xf00
	s_cselect_b32 s29, s42, s27
	s_cselect_b32 s28, s19, s26
	s_cselect_b32 s27, s43, s50
	s_cselect_b32 s26, s21, s49
	s_add_i32 s49, 0, 0x14000
	v_add_u32_e32 v144, s51, v171
	v_add_u32_e32 v168, s49, v171
	ds_read_b128 v[132:135], v144
	ds_read_b128 v[136:139], v144 offset:1024
	ds_read_b128 v[140:143], v144 offset:2048
	ds_read_b128 v[144:147], v144 offset:3072
	ds_read_b128 v[148:151], v168
	ds_read_b128 v[164:167], v168 offset:1024
	ds_read_b128 v[174:177], v168 offset:2048
	ds_read_b128 v[178:181], v168 offset:3072
	v_lshl_add_u64 v[168:169], v[128:129], 0, s[8:9]
	s_add_i32 m0, s31, 0xc000
	ds_read_b128 v[182:185], v172
	ds_read_b128 v[186:189], v172 offset:1024
	ds_read_b128 v[194:197], v172 offset:2048
	ds_read_b128 v[198:201], v172 offset:3072
	ds_read_b128 v[202:205], v172 offset:4096
	ds_read_b128 v[206:209], v172 offset:5120
	ds_read_b128 v[216:219], v172 offset:6144
	ds_read_b128 v[220:223], v172 offset:7168
	global_load_lds_dwordx4 v[168:169], off
	v_lshl_add_u64 v[168:169], v[130:131], 0, s[8:9]
	s_add_i32 m0, s31, 0xe000
	s_nop 0
	global_load_lds_dwordx4 v[168:169], off
	s_waitcnt vmcnt(8)
	s_waitcnt lgkmcnt(0)
	s_setprio 1
	s_barrier
	v_mfma_f32_16x16x32_bf16 v[124:127], v[132:135], v[182:185], v[124:127]
	v_mfma_f32_16x16x32_bf16 v[120:123], v[140:143], v[182:185], v[120:123]
	v_mfma_f32_16x16x32_bf16 v[108:111], v[132:135], v[194:197], v[108:111]
	v_mfma_f32_16x16x32_bf16 v[104:107], v[140:143], v[194:197], v[104:107]
	v_mfma_f32_16x16x32_bf16 v[92:95], v[132:135], v[202:205], v[92:95]
	v_mfma_f32_16x16x32_bf16 v[88:91], v[140:143], v[202:205], v[88:91]
	v_mfma_f32_16x16x32_bf16 v[76:79], v[132:135], v[216:219], v[76:79]
	v_mfma_f32_16x16x32_bf16 v[72:75], v[140:143], v[216:219], v[72:75]
	v_mfma_f32_16x16x32_bf16 v[124:127], v[136:139], v[186:189], v[124:127]
	v_mfma_f32_16x16x32_bf16 v[120:123], v[144:147], v[186:189], v[120:123]
	v_mfma_f32_16x16x32_bf16 v[108:111], v[136:139], v[198:201], v[108:111]
	v_mfma_f32_16x16x32_bf16 v[104:107], v[144:147], v[198:201], v[104:107]
	v_mfma_f32_16x16x32_bf16 v[92:95], v[136:139], v[206:209], v[92:95]
	v_mfma_f32_16x16x32_bf16 v[88:91], v[144:147], v[206:209], v[88:91]
	v_mfma_f32_16x16x32_bf16 v[76:79], v[136:139], v[220:223], v[76:79]
	v_mfma_f32_16x16x32_bf16 v[72:75], v[144:147], v[220:223], v[72:75]
	s_setprio 0
	s_setprio 1
	v_mfma_f32_16x16x32_bf16 v[116:119], v[148:151], v[182:185], v[116:119]
	v_mfma_f32_16x16x32_bf16 v[112:115], v[174:177], v[182:185], v[112:115]
	v_mfma_f32_16x16x32_bf16 v[100:103], v[148:151], v[194:197], v[100:103]
	v_mfma_f32_16x16x32_bf16 v[96:99], v[174:177], v[194:197], v[96:99]
	v_mfma_f32_16x16x32_bf16 v[84:87], v[148:151], v[202:205], v[84:87]
	v_mfma_f32_16x16x32_bf16 v[80:83], v[174:177], v[202:205], v[80:83]
	v_mfma_f32_16x16x32_bf16 v[68:71], v[148:151], v[216:219], v[68:71]
	v_mfma_f32_16x16x32_bf16 v[64:67], v[174:177], v[216:219], v[64:67]
	v_mfma_f32_16x16x32_bf16 v[116:119], v[164:167], v[186:189], v[116:119]
	v_mfma_f32_16x16x32_bf16 v[112:115], v[178:181], v[186:189], v[112:115]
	v_mfma_f32_16x16x32_bf16 v[100:103], v[164:167], v[198:201], v[100:103]
	v_mfma_f32_16x16x32_bf16 v[96:99], v[178:181], v[198:201], v[96:99]
	v_mfma_f32_16x16x32_bf16 v[84:87], v[164:167], v[206:209], v[84:87]
	v_mfma_f32_16x16x32_bf16 v[80:83], v[178:181], v[206:209], v[80:83]
	v_mfma_f32_16x16x32_bf16 v[68:71], v[164:167], v[220:223], v[68:71]
	v_mfma_f32_16x16x32_bf16 v[64:67], v[178:181], v[220:223], v[64:67]
	s_barrier
	s_setprio 0
	s_add_i32 s50, s51, s30
	v_lshl_add_u64 v[168:169], s[26:27], 0, v[192:193]
	s_mov_b32 m0, s50
	ds_read_b128 v[182:185], v172 offset:16384
	ds_read_b128 v[186:189], v172 offset:17408
	ds_read_b128 v[194:197], v172 offset:18432
	ds_read_b128 v[198:201], v172 offset:19456
	ds_read_b128 v[202:205], v172 offset:20480
	ds_read_b128 v[206:209], v172 offset:21504
	ds_read_b128 v[216:219], v172 offset:22528
	ds_read_b128 v[220:223], v172 offset:23552
	global_load_lds_dwordx4 v[168:169], off
	s_add_i32 m0, s50, 0x2000
	s_add_u32 s50, s26, 0x80000
	v_lshl_add_u64 v[190:191], s[26:27], 0, v[152:153]
	s_addc_u32 s51, s27, 0
	s_add_i32 s49, s49, s30
	global_load_lds_dwordx4 v[190:191], off
	v_lshl_add_u64 v[212:213], s[50:51], 0, v[192:193]
	s_mov_b32 m0, s49
	v_lshl_add_u64 v[214:215], s[28:29], 0, v[154:155]
	global_load_lds_dwordx4 v[212:213], off
	v_lshl_add_u64 v[212:213], s[50:51], 0, v[152:153]
	s_add_i32 m0, s49, 0x2000
	s_nop 0
	global_load_lds_dwordx4 v[212:213], off
	v_lshl_add_u64 v[212:213], s[28:29], 0, v[156:157]
	s_mov_b32 m0, s31
	s_nop 0
	global_load_lds_dwordx4 v[212:213], off
	s_mov_b32 m0, s34
	s_nop 0
	global_load_lds_dwordx4 v[214:215], off
	s_waitcnt vmcnt(8)
	s_waitcnt lgkmcnt(0)
	s_setprio 1
	s_barrier
; #define STAGE_A(bufoff, gbase) STAGEX(bufoff, gbase, voffA)
; #define STAGE_B(bufoff, gbase) STAGEX(bufoff, gbase, voffB)
; #define LDA(dst, b, h) do { _Pragma("unroll") for (int m = 0; m < 4; ++m) _Pragma("unroll") for (int k = 0; k < 2; ++k) dst[m][k] = *(const __attribute__((address_space(3))) bf16x8*)(lds + SA(b, h) + aoff + m * 2048 + k * 1024); } while (0)
; #define LDB(dst, b, h) do { _Pragma("unroll") for (int n = 0; n < 2; ++n) _Pragma("unroll") for (int k = 0; k < 2; ++k) dst[n][k] = *(const __attribute__((address_space(3))) bf16x8*)(lds + SB_(b, h) + boff + n * 2048 + k * 1024); } while (0)
; #define MMA(ai, bj, At, Bt_) do { __builtin_amdgcn_s_setprio(1); _Pragma("unroll") for (int m = 0; m < 4; ++m) _Pragma("unroll") for (int n = 0; n < 2; ++n) _Pragma("unroll") for (int k = 0; k < 2; ++k) \
;       acc[ai][bj][m][n] = __builtin_amdgcn_mfma_f32_16x16x32_bf16(Bt_[n][k], At[m][k], acc[ai][bj][m][n], 0, 0, 0); \
;     __builtin_amdgcn_s_setprio(0); } while (0)
; #define WAIT_V(n) asm volatile("s_waitcnt vmcnt(" #n ")" ::: "memory")
; #define WAIT_L(n) asm volatile("s_waitcnt lgkmcnt(" #n ")" ::: "memory")
; #define BAR __builtin_amdgcn_s_barrier()
; #define SCHED __builtin_amdgcn_sched_barrier(0)
; template <int MODE>
; DEV void gemm_phase(const bf16_t* __restrict__ A, const bf16_t* __restrict__ Bt, int M, int N, int K, bf16_t* __restrict__ Out, int ldo,
;                     const float* __restrict__ rstd, const float* __restrict__ rope) {
;     ...
;       LDB(B0, 0, 0); LDB(B1, 0, 1); SCHED; LDA(At, 0, 0); STAGE_A(SA(1, 1), a1 + hstep);
;       WAIT_V(8); WAIT_L(0); BAR; MMA(0, 0, At, B0); MMA(0, 1, At, B1); BAR; SCHED;
;       LDA(At, 0, 1); STAGE_B(SB_(0, 0), b2); STAGE_B(SB_(0, 1), b2 + hstep); STAGE_A(SA(0, 0), a2);
;       WAIT_V(8); WAIT_L(0); BAR; MMA(1, 0, At, B0); MMA(1, 1, At, B1); BAR; SCHED;
;       LDB(B0, 1, 0); LDB(B1, 1, 1); SCHED; LDA(At, 1, 0); STAGE_A(SA(0, 1), a2 + hstep);
;       WAIT_V(8); WAIT_L(0); BAR; MMA(0, 0, At, B0); MMA(0, 1, At, B1); BAR; SCHED;
;       LDA(At, 1, 1); STAGE_B(SB_(1, 0), b3); STAGE_B(SB_(1, 1), b3 + hstep); STAGE_A(SA(1, 0), a3);
;       WAIT_V(8); WAIT_L(0); BAR; MMA(1, 0, At, B0); MMA(1, 1, At, B1); BAR; SCHED;
	v_mfma_f32_16x16x32_bf16 v[60:63], v[132:135], v[182:185], v[60:63]
	v_mfma_f32_16x16x32_bf16 v[56:59], v[140:143], v[182:185], v[56:59]
	v_mfma_f32_16x16x32_bf16 v[44:47], v[132:135], v[194:197], v[44:47]
	v_mfma_f32_16x16x32_bf16 v[40:43], v[140:143], v[194:197], v[40:43]
	v_mfma_f32_16x16x32_bf16 v[28:31], v[132:135], v[202:205], v[28:31]
	v_mfma_f32_16x16x32_bf16 v[24:27], v[140:143], v[202:205], v[24:27]
	v_mfma_f32_16x16x32_bf16 v[12:15], v[132:135], v[216:219], v[12:15]
	v_mfma_f32_16x16x32_bf16 v[8:11], v[140:143], v[216:219], v[8:11]
	v_mfma_f32_16x16x32_bf16 v[60:63], v[136:139], v[186:189], v[60:63]
	v_mfma_f32_16x16x32_bf16 v[56:59], v[144:147], v[186:189], v[56:59]
	v_mfma_f32_16x16x32_bf16 v[44:47], v[136:139], v[198:201], v[44:47]
	v_mfma_f32_16x16x32_bf16 v[40:43], v[144:147], v[198:201], v[40:43]
	v_mfma_f32_16x16x32_bf16 v[28:31], v[136:139], v[206:209], v[28:31]
	v_mfma_f32_16x16x32_bf16 v[24:27], v[144:147], v[206:209], v[24:27]
	v_mfma_f32_16x16x32_bf16 v[12:15], v[136:139], v[220:223], v[12:15]
	v_mfma_f32_16x16x32_bf16 v[8:11], v[144:147], v[220:223], v[8:11]
	s_setprio 0
	s_setprio 1
	v_mfma_f32_16x16x32_bf16 v[52:55], v[148:151], v[182:185], v[52:55]
	v_mfma_f32_16x16x32_bf16 v[48:51], v[174:177], v[182:185], v[48:51]
	v_mfma_f32_16x16x32_bf16 v[36:39], v[148:151], v[194:197], v[36:39]
	v_mfma_f32_16x16x32_bf16 v[32:35], v[174:177], v[194:197], v[32:35]
	v_mfma_f32_16x16x32_bf16 v[20:23], v[148:151], v[202:205], v[20:23]
	v_mfma_f32_16x16x32_bf16 v[16:19], v[174:177], v[202:205], v[16:19]
	v_mfma_f32_16x16x32_bf16 v[4:7], v[148:151], v[216:219], v[4:7]
	v_mfma_f32_16x16x32_bf16 v[0:3], v[174:177], v[216:219], v[0:3]
	v_mfma_f32_16x16x32_bf16 v[52:55], v[164:167], v[186:189], v[52:55]
	v_mfma_f32_16x16x32_bf16 v[48:51], v[178:181], v[186:189], v[48:51]
	v_mfma_f32_16x16x32_bf16 v[36:39], v[164:167], v[198:201], v[36:39]
	v_mfma_f32_16x16x32_bf16 v[32:35], v[178:181], v[198:201], v[32:35]
	v_mfma_f32_16x16x32_bf16 v[20:23], v[164:167], v[206:209], v[20:23]
	v_mfma_f32_16x16x32_bf16 v[16:19], v[178:181], v[206:209], v[16:19]
	v_mfma_f32_16x16x32_bf16 v[4:7], v[164:167], v[220:223], v[4:7]
	v_mfma_f32_16x16x32_bf16 v[0:3], v[178:181], v[220:223], v[0:3]
	s_barrier
	s_setprio 0
	s_add_i32 s49, 0, 0x18000
	s_add_i32 s50, 0, 0x1c000
	v_add_u32_e32 v144, s49, v171
	v_add_u32_e32 v173, s50, v171
	ds_read_b128 v[132:135], v144
	ds_read_b128 v[136:139], v144 offset:1024
	ds_read_b128 v[140:143], v144 offset:2048
	ds_read_b128 v[144:147], v144 offset:3072
	ds_read_b128 v[148:151], v173
	ds_read_b128 v[164:167], v173 offset:1024
	ds_read_b128 v[174:177], v173 offset:2048
	ds_read_b128 v[178:181], v173 offset:3072
	s_add_u32 s28, s28, 0x80000
	s_addc_u32 s29, s29, 0
	s_mov_b32 m0, s35
	v_lshl_add_u64 v[224:225], s[28:29], 0, v[156:157]
	ds_read_b128 v[182:185], v172 offset:32768
	ds_read_b128 v[186:189], v172 offset:33792
	ds_read_b128 v[194:197], v172 offset:34816
	ds_read_b128 v[198:201], v172 offset:35840
	ds_read_b128 v[202:205], v172 offset:36864
	ds_read_b128 v[206:209], v172 offset:37888
	ds_read_b128 v[216:219], v172 offset:38912
	ds_read_b128 v[220:223], v172 offset:39936
	global_load_lds_dwordx4 v[224:225], off
	v_lshl_add_u64 v[224:225], s[28:29], 0, v[154:155]
	s_mov_b32 m0, s36
	s_nop 0
	global_load_lds_dwordx4 v[224:225], off
	s_waitcnt vmcnt(8)
	s_waitcnt lgkmcnt(0)
	s_setprio 1
	s_barrier
	v_mfma_f32_16x16x32_bf16 v[124:127], v[132:135], v[182:185], v[124:127]
	v_mfma_f32_16x16x32_bf16 v[120:123], v[140:143], v[182:185], v[120:123]
	v_mfma_f32_16x16x32_bf16 v[108:111], v[132:135], v[194:197], v[108:111]
	v_mfma_f32_16x16x32_bf16 v[104:107], v[140:143], v[194:197], v[104:107]
	v_mfma_f32_16x16x32_bf16 v[92:95], v[132:135], v[202:205], v[92:95]
	v_mfma_f32_16x16x32_bf16 v[88:91], v[140:143], v[202:205], v[88:91]
	v_mfma_f32_16x16x32_bf16 v[76:79], v[132:135], v[216:219], v[76:79]
	v_mfma_f32_16x16x32_bf16 v[72:75], v[140:143], v[216:219], v[72:75]
	v_mfma_f32_16x16x32_bf16 v[124:127], v[136:139], v[186:189], v[124:127]
	v_mfma_f32_16x16x32_bf16 v[120:123], v[144:147], v[186:189], v[120:123]
	v_mfma_f32_16x16x32_bf16 v[108:111], v[136:139], v[198:201], v[108:111]
	v_mfma_f32_16x16x32_bf16 v[104:107], v[144:147], v[198:201], v[104:107]
	v_mfma_f32_16x16x32_bf16 v[92:95], v[136:139], v[206:209], v[92:95]
	v_mfma_f32_16x16x32_bf16 v[88:91], v[144:147], v[206:209], v[88:91]
	v_mfma_f32_16x16x32_bf16 v[76:79], v[136:139], v[220:223], v[76:79]
	v_mfma_f32_16x16x32_bf16 v[72:75], v[144:147], v[220:223], v[72:75]
	s_setprio 0
	s_setprio 1
	v_mfma_f32_16x16x32_bf16 v[116:119], v[148:151], v[182:185], v[116:119]
	v_mfma_f32_16x16x32_bf16 v[112:115], v[174:177], v[182:185], v[112:115]
	v_mfma_f32_16x16x32_bf16 v[100:103], v[148:151], v[194:197], v[100:103]
	v_mfma_f32_16x16x32_bf16 v[96:99], v[174:177], v[194:197], v[96:99]
	v_mfma_f32_16x16x32_bf16 v[84:87], v[148:151], v[202:205], v[84:87]
	v_mfma_f32_16x16x32_bf16 v[80:83], v[174:177], v[202:205], v[80:83]
	v_mfma_f32_16x16x32_bf16 v[68:71], v[148:151], v[216:219], v[68:71]
	v_mfma_f32_16x16x32_bf16 v[64:67], v[174:177], v[216:219], v[64:67]
	v_mfma_f32_16x16x32_bf16 v[116:119], v[164:167], v[186:189], v[116:119]
	v_mfma_f32_16x16x32_bf16 v[112:115], v[178:181], v[186:189], v[112:115]
	v_mfma_f32_16x16x32_bf16 v[100:103], v[164:167], v[198:201], v[100:103]
	v_mfma_f32_16x16x32_bf16 v[96:99], v[178:181], v[198:201], v[96:99]
	v_mfma_f32_16x16x32_bf16 v[84:87], v[164:167], v[206:209], v[84:87]
	v_mfma_f32_16x16x32_bf16 v[80:83], v[178:181], v[206:209], v[80:83]
	v_mfma_f32_16x16x32_bf16 v[68:71], v[164:167], v[220:223], v[68:71]
	v_mfma_f32_16x16x32_bf16 v[64:67], v[178:181], v[220:223], v[64:67]
	s_barrier
; #define STAGE_A(bufoff, gbase) STAGEX(bufoff, gbase, voffA)
; #define STAGE_B(bufoff, gbase) STAGEX(bufoff, gbase, voffB)
; #define LDA(dst, b, h) do { _Pragma("unroll") for (int m = 0; m < 4; ++m) _Pragma("unroll") for (int k = 0; k < 2; ++k) dst[m][k] = *(const __attribute__((address_space(3))) bf16x8*)(lds + SA(b, h) + aoff + m * 2048 + k * 1024); } while (0)
; #define LDB(dst, b, h) do { _Pragma("unroll") for (int n = 0; n < 2; ++n) _Pragma("unroll") for (int k = 0; k < 2; ++k) dst[n][k] = *(const __attribute__((address_space(3))) bf16x8*)(lds + SB_(b, h) + boff + n * 2048 + k * 1024); } while (0)
; #define MMA(ai, bj, At, Bt_) do { __builtin_amdgcn_s_setprio(1); _Pragma("unroll") for (int m = 0; m < 4; ++m) _Pragma("unroll") for (int n = 0; n < 2; ++n) _Pragma("unroll") for (int k = 0; k < 2; ++k) \
;       acc[ai][bj][m][n] = __builtin_amdgcn_mfma_f32_16x16x32_bf16(Bt_[n][k], At[m][k], acc[ai][bj][m][n], 0, 0, 0); \
;     __builtin_amdgcn_s_setprio(0); } while (0)
; #define WAIT_V(n) asm volatile("s_waitcnt vmcnt(" #n ")" ::: "memory")
; #define WAIT_L(n) asm volatile("s_waitcnt lgkmcnt(" #n ")" ::: "memory")
; #define BAR __builtin_amdgcn_s_barrier()
; #define SCHED __builtin_amdgcn_sched_barrier(0)
; template <int MODE>
; DEV void gemm_phase(const bf16_t* __restrict__ A, const bf16_t* __restrict__ Bt, int M, int N, int K, bf16_t* __restrict__ Out, int ldo,
;                     const float* __restrict__ rstd, const float* __restrict__ rope) {
;     ...
;       LDA(At, 0, 1); STAGE_B(SB_(0, 0), b2); STAGE_B(SB_(0, 1), b2 + hstep); STAGE_A(SA(0, 0), a2);
;       WAIT_V(8); WAIT_L(0); BAR; MMA(1, 0, At, B0); MMA(1, 1, At, B1); BAR; SCHED;
;       LDB(B0, 1, 0); LDB(B1, 1, 1); SCHED; LDA(At, 1, 0); STAGE_A(SA(0, 1), a2 + hstep);
;       WAIT_V(8); WAIT_L(0); BAR; MMA(0, 0, At, B0); MMA(0, 1, At, B1); BAR; SCHED;
;       LDA(At, 1, 1); STAGE_B(SB_(1, 0), b3); STAGE_B(SB_(1, 1), b3 + hstep); STAGE_A(SA(1, 0), a3);
;       WAIT_V(8); WAIT_L(0); BAR; MMA(1, 0, At, B0); MMA(1, 1, At, B1); BAR; SCHED;
;     }
;     if (wr == 0) BAR;
	s_setprio 0
	s_add_i32 s28, s49, s30
	v_lshl_add_u64 v[168:169], v[168:169], 0, s[88:89]
	s_mov_b32 m0, s28
	ds_read_b128 v[182:185], v172 offset:49152
	ds_read_b128 v[186:189], v172 offset:50176
	ds_read_b128 v[194:197], v172 offset:51200
	ds_read_b128 v[198:201], v172 offset:52224
	ds_read_b128 v[202:205], v172 offset:53248
	ds_read_b128 v[206:209], v172 offset:54272
	ds_read_b128 v[216:219], v172 offset:55296
	ds_read_b128 v[220:223], v172 offset:56320
	global_load_lds_dwordx4 v[168:169], off
	s_add_i32 m0, s28, 0x2000
	s_add_u32 s26, s26, 0x80080
	v_lshl_add_u64 v[168:169], v[190:191], 0, s[88:89]
	s_addc_u32 s27, s27, 0
	s_add_i32 s28, s50, s30
	global_load_lds_dwordx4 v[168:169], off
	v_lshl_add_u64 v[168:169], s[26:27], 0, v[192:193]
	s_mov_b32 m0, s28
	s_nop 0
	global_load_lds_dwordx4 v[168:169], off
	v_lshl_add_u64 v[168:169], s[26:27], 0, v[152:153]
	s_add_i32 m0, s28, 0x2000
	s_nop 0
	global_load_lds_dwordx4 v[168:169], off
	v_lshl_add_u64 v[168:169], v[212:213], 0, s[88:89]
	s_mov_b32 m0, s37
	s_nop 0
	global_load_lds_dwordx4 v[168:169], off
	v_lshl_add_u64 v[168:169], v[214:215], 0, s[88:89]
	s_mov_b32 m0, s38
	s_nop 0
	global_load_lds_dwordx4 v[168:169], off
	s_waitcnt vmcnt(8)
	s_waitcnt lgkmcnt(0)
	s_setprio 1
	s_barrier
	v_mfma_f32_16x16x32_bf16 v[60:63], v[132:135], v[182:185], v[60:63]
	v_mfma_f32_16x16x32_bf16 v[56:59], v[140:143], v[182:185], v[56:59]
	v_mfma_f32_16x16x32_bf16 v[44:47], v[132:135], v[194:197], v[44:47]
	v_mfma_f32_16x16x32_bf16 v[40:43], v[140:143], v[194:197], v[40:43]
	v_mfma_f32_16x16x32_bf16 v[28:31], v[132:135], v[202:205], v[28:31]
	v_mfma_f32_16x16x32_bf16 v[24:27], v[140:143], v[202:205], v[24:27]
	v_mfma_f32_16x16x32_bf16 v[12:15], v[132:135], v[216:219], v[12:15]
	v_mfma_f32_16x16x32_bf16 v[8:11], v[140:143], v[216:219], v[8:11]
	v_mfma_f32_16x16x32_bf16 v[60:63], v[136:139], v[186:189], v[60:63]
	v_mfma_f32_16x16x32_bf16 v[56:59], v[144:147], v[186:189], v[56:59]
	v_mfma_f32_16x16x32_bf16 v[44:47], v[136:139], v[198:201], v[44:47]
	v_mfma_f32_16x16x32_bf16 v[40:43], v[144:147], v[198:201], v[40:43]
	v_mfma_f32_16x16x32_bf16 v[28:31], v[136:139], v[206:209], v[28:31]
	v_mfma_f32_16x16x32_bf16 v[24:27], v[144:147], v[206:209], v[24:27]
	v_mfma_f32_16x16x32_bf16 v[12:15], v[136:139], v[220:223], v[12:15]
	v_mfma_f32_16x16x32_bf16 v[8:11], v[144:147], v[220:223], v[8:11]
	s_setprio 0
	s_setprio 1
	v_mfma_f32_16x16x32_bf16 v[52:55], v[148:151], v[182:185], v[52:55]
	v_mfma_f32_16x16x32_bf16 v[48:51], v[174:177], v[182:185], v[48:51]
	v_mfma_f32_16x16x32_bf16 v[36:39], v[148:151], v[194:197], v[36:39]
	v_mfma_f32_16x16x32_bf16 v[32:35], v[174:177], v[194:197], v[32:35]
	v_mfma_f32_16x16x32_bf16 v[20:23], v[148:151], v[202:205], v[20:23]
	v_mfma_f32_16x16x32_bf16 v[16:19], v[174:177], v[202:205], v[16:19]
	v_mfma_f32_16x16x32_bf16 v[4:7], v[148:151], v[216:219], v[4:7]
	v_mfma_f32_16x16x32_bf16 v[0:3], v[174:177], v[216:219], v[0:3]
	v_mfma_f32_16x16x32_bf16 v[52:55], v[164:167], v[186:189], v[52:55]
	v_mfma_f32_16x16x32_bf16 v[48:51], v[178:181], v[186:189], v[48:51]
	v_mfma_f32_16x16x32_bf16 v[36:39], v[164:167], v[198:201], v[36:39]
	v_mfma_f32_16x16x32_bf16 v[32:35], v[178:181], v[198:201], v[32:35]
	v_mfma_f32_16x16x32_bf16 v[20:23], v[164:167], v[206:209], v[20:23]
	v_mfma_f32_16x16x32_bf16 v[16:19], v[178:181], v[206:209], v[16:19]
	v_mfma_f32_16x16x32_bf16 v[4:7], v[164:167], v[220:223], v[4:7]
	v_mfma_f32_16x16x32_bf16 v[0:3], v[178:181], v[220:223], v[0:3]
	s_barrier
	s_setprio 0
	s_add_i32 s48, s48, 2
	s_add_u32 s8, s8, 0x100
	s_addc_u32 s9, s9, 0
	s_cmp_gt_u32 s48, 29
	s_cbranch_scc0 .LBB0_128
	s_and_b64 vcc, exec, s[12:13]
	s_cbranch_vccz .LBB0_131
	s_barrier

; #define STAGE_A(bufoff, gbase) STAGEX(bufoff, gbase, voffA)
; #define STAGE_B(bufoff, gbase) STAGEX(bufoff, gbase, voffB)
; #define LDA(dst, b, h) do { _Pragma("unroll") for (int m = 0; m < 4; ++m) _Pragma("unroll") for (int k = 0; k < 2; ++k) dst[m][k] = *(const __attribute__((address_space(3))) bf16x8*)(lds + SA(b, h) + aoff + m * 2048 + k * 1024); } while (0)
; #define LDB(dst, b, h) do { _Pragma("unroll") for (int n = 0; n < 2; ++n) _Pragma("unroll") for (int k = 0; k < 2; ++k) dst[n][k] = *(const __attribute__((address_space(3))) bf16x8*)(lds + SB_(b, h) + boff + n * 2048 + k * 1024); } while (0)
; #define MMA(ai, bj, At, Bt_) do { __builtin_amdgcn_s_setprio(1); _Pragma("unroll") for (int m = 0; m < 4; ++m) _Pragma("unroll") for (int n = 0; n < 2; ++n) _Pragma("unroll") for (int k = 0; k < 2; ++k) \
;       acc[ai][bj][m][n] = __builtin_amdgcn_mfma_f32_16x16x32_bf16(Bt_[n][k], At[m][k], acc[ai][bj][m][n], 0, 0, 0); \
;     __builtin_amdgcn_s_setprio(0); } while (0)
; #define WAIT_V(n) asm volatile("s_waitcnt vmcnt(" #n ")" ::: "memory")
; #define WAIT_L(n) asm volatile("s_waitcnt lgkmcnt(" #n ")" ::: "memory")
; #define BAR __builtin_amdgcn_s_barrier()
; #define SCHED __builtin_amdgcn_sched_barrier(0)
; template <int MODE>
; DEV void gemm_phase(const bf16_t* __restrict__ A, const bf16_t* __restrict__ Bt, int M, int N, int K, bf16_t* __restrict__ Out, int ldo,
;                     const float* __restrict__ rstd, const float* __restrict__ rope) {
;     ...
;     for (int t = 0; t < nt; t += 2) {
;       const bool last = (t == nt - 2);
;       const char* a1 = cA + (size_t)(t + 1) * 128;
;       const char* a2 = last ? nA : cA + (size_t)(t + 2) * 128; const char* b2 = last ? nB : cB + (size_t)(t + 2) * 128;
;       const char* a3 = a2 + 128; const char* b3 = b2 + 128;
;       LDB(B0, 0, 0); LDB(B1, 0, 1); SCHED; LDA(At, 0, 0); STAGE_A(SA(1, 1), a1 + hstep);
;       WAIT_V(8); WAIT_L(0); BAR; MMA(0, 0, At, B0); MMA(0, 1, At, B1); BAR; SCHED;
;       LDA(At, 0, 1); STAGE_B(SB_(0, 0), b2); STAGE_B(SB_(0, 1), b2 + hstep); STAGE_A(SA(0, 0), a2);
;       WAIT_V(8); WAIT_L(0); BAR; MMA(1, 0, At, B0); MMA(1, 1, At, B1); BAR; SCHED;
.LBB0_493:
	s_add_u32 s20, s18, 0xfff80080
	s_addc_u32 s21, s19, -1
	s_add_i32 s39, 0, 0x10000
	s_cmp_eq_u32 s38, 28
	s_cselect_b32 s23, s15, s21
	s_cselect_b32 s22, s14, s20
	v_add_u32_e32 v143, s39, v141
	s_cselect_b32 s21, s13, s37
	s_cselect_b32 s20, s11, s36
	s_add_i32 s42, 0, 0x14000
	ds_read_b128 v[144:147], v143
	ds_read_b128 v[148:151], v143 offset:1024
	ds_read_b128 v[152:155], v143 offset:2048
	ds_read_b128 v[156:159], v143 offset:3072
	v_add_u32_e32 v143, s42, v141
	ds_read_b128 v[160:163], v143
	ds_read_b128 v[164:167], v143 offset:1024
	ds_read_b128 v[168:171], v143 offset:2048
	ds_read_b128 v[172:175], v143 offset:3072
	v_lshl_add_u64 v[212:213], s[18:19], 0, v[136:137]
	s_add_i32 m0, s25, 0xc000
	ds_read_b128 v[176:179], v142
	ds_read_b128 v[180:183], v142 offset:1024
	ds_read_b128 v[184:187], v142 offset:2048
	ds_read_b128 v[188:191], v142 offset:3072
	ds_read_b128 v[194:197], v142 offset:4096
	ds_read_b128 v[198:201], v142 offset:5120
	ds_read_b128 v[202:205], v142 offset:6144
	ds_read_b128 v[206:209], v142 offset:7168
	global_load_lds_dwordx4 v[212:213], off
	v_lshl_add_u64 v[212:213], s[18:19], 0, v[138:139]
	s_add_i32 m0, s25, 0xe000
	s_nop 0
	global_load_lds_dwordx4 v[212:213], off
	s_waitcnt vmcnt(8)
	s_waitcnt lgkmcnt(0)
	s_setprio 1
	s_barrier
	v_mfma_f32_16x16x32_bf16 v[124:127], v[144:147], v[176:179], v[124:127]
	v_mfma_f32_16x16x32_bf16 v[120:123], v[152:155], v[176:179], v[120:123]
	v_mfma_f32_16x16x32_bf16 v[116:119], v[144:147], v[184:187], v[116:119]
	v_mfma_f32_16x16x32_bf16 v[112:115], v[152:155], v[184:187], v[112:115]
	v_mfma_f32_16x16x32_bf16 v[100:103], v[144:147], v[194:197], v[100:103]
	v_mfma_f32_16x16x32_bf16 v[96:99], v[152:155], v[194:197], v[96:99]
	v_mfma_f32_16x16x32_bf16 v[84:87], v[144:147], v[202:205], v[84:87]
	v_mfma_f32_16x16x32_bf16 v[80:83], v[152:155], v[202:205], v[80:83]
	v_mfma_f32_16x16x32_bf16 v[124:127], v[148:151], v[180:183], v[124:127]
	v_mfma_f32_16x16x32_bf16 v[120:123], v[156:159], v[180:183], v[120:123]
	v_mfma_f32_16x16x32_bf16 v[116:119], v[148:151], v[188:191], v[116:119]
	v_mfma_f32_16x16x32_bf16 v[112:115], v[156:159], v[188:191], v[112:115]
	v_mfma_f32_16x16x32_bf16 v[100:103], v[148:151], v[198:201], v[100:103]
	v_mfma_f32_16x16x32_bf16 v[96:99], v[156:159], v[198:201], v[96:99]
	v_mfma_f32_16x16x32_bf16 v[84:87], v[148:151], v[206:209], v[84:87]
	v_mfma_f32_16x16x32_bf16 v[80:83], v[156:159], v[206:209], v[80:83]
	s_setprio 0
	s_setprio 1
	v_mfma_f32_16x16x32_bf16 v[108:111], v[160:163], v[176:179], v[108:111]
	v_mfma_f32_16x16x32_bf16 v[104:107], v[168:171], v[176:179], v[104:107]
	v_mfma_f32_16x16x32_bf16 v[92:95], v[160:163], v[184:187], v[92:95]
	v_mfma_f32_16x16x32_bf16 v[88:91], v[168:171], v[184:187], v[88:91]
	v_mfma_f32_16x16x32_bf16 v[76:79], v[160:163], v[194:197], v[76:79]
	v_mfma_f32_16x16x32_bf16 v[72:75], v[168:171], v[194:197], v[72:75]
	v_mfma_f32_16x16x32_bf16 v[68:71], v[160:163], v[202:205], v[68:71]
	v_mfma_f32_16x16x32_bf16 v[64:67], v[168:171], v[202:205], v[64:67]
	v_mfma_f32_16x16x32_bf16 v[108:111], v[164:167], v[180:183], v[108:111]
	v_mfma_f32_16x16x32_bf16 v[104:107], v[172:175], v[180:183], v[104:107]
	v_mfma_f32_16x16x32_bf16 v[92:95], v[164:167], v[188:191], v[92:95]
	v_mfma_f32_16x16x32_bf16 v[88:91], v[172:175], v[188:191], v[88:91]
	v_mfma_f32_16x16x32_bf16 v[76:79], v[164:167], v[198:201], v[76:79]
	v_mfma_f32_16x16x32_bf16 v[72:75], v[172:175], v[198:201], v[72:75]
	v_mfma_f32_16x16x32_bf16 v[68:71], v[164:167], v[206:209], v[68:71]
	v_mfma_f32_16x16x32_bf16 v[64:67], v[172:175], v[206:209], v[64:67]
	s_barrier
	s_setprio 0
	s_add_i32 s39, s39, s24
	v_lshl_add_u64 v[212:213], s[20:21], 0, v[192:193]
	s_mov_b32 m0, s39
	ds_read_b128 v[176:179], v142 offset:16384
	ds_read_b128 v[180:183], v142 offset:17408
	ds_read_b128 v[184:187], v142 offset:18432
	ds_read_b128 v[188:191], v142 offset:19456
	ds_read_b128 v[194:197], v142 offset:20480
	ds_read_b128 v[198:201], v142 offset:21504
	ds_read_b128 v[202:205], v142 offset:22528
	ds_read_b128 v[206:209], v142 offset:23552
	global_load_lds_dwordx4 v[212:213], off
	s_add_i32 m0, s39, 0x2000
	s_add_u32 s40, s20, 0x80000
	v_lshl_add_u64 v[214:215], s[20:21], 0, v[128:129]
	s_addc_u32 s41, s21, 0
	s_add_i32 s39, s42, s24
	global_load_lds_dwordx4 v[214:215], off
	v_lshl_add_u64 v[222:223], s[40:41], 0, v[192:193]
	s_mov_b32 m0, s39
	v_lshl_add_u64 v[224:225], s[22:23], 0, v[130:131]
	global_load_lds_dwordx4 v[222:223], off
	v_lshl_add_u64 v[222:223], s[40:41], 0, v[128:129]
	s_add_i32 m0, s39, 0x2000
	s_nop 0
	global_load_lds_dwordx4 v[222:223], off
	v_lshl_add_u64 v[222:223], s[22:23], 0, v[132:133]
	s_mov_b32 m0, s25
	s_nop 0
	global_load_lds_dwordx4 v[222:223], off
	s_mov_b32 m0, s26
	s_nop 0
	global_load_lds_dwordx4 v[224:225], off
	s_waitcnt vmcnt(8)
	s_waitcnt lgkmcnt(0)
	s_setprio 1
	s_barrier
; #define STAGE_A(bufoff, gbase) STAGEX(bufoff, gbase, voffA)
; #define STAGE_B(bufoff, gbase) STAGEX(bufoff, gbase, voffB)
; #define LDA(dst, b, h) do { _Pragma("unroll") for (int m = 0; m < 4; ++m) _Pragma("unroll") for (int k = 0; k < 2; ++k) dst[m][k] = *(const __attribute__((address_space(3))) bf16x8*)(lds + SA(b, h) + aoff + m * 2048 + k * 1024); } while (0)
; #define LDB(dst, b, h) do { _Pragma("unroll") for (int n = 0; n < 2; ++n) _Pragma("unroll") for (int k = 0; k < 2; ++k) dst[n][k] = *(const __attribute__((address_space(3))) bf16x8*)(lds + SB_(b, h) + boff + n * 2048 + k * 1024); } while (0)
; #define MMA(ai, bj, At, Bt_) do { __builtin_amdgcn_s_setprio(1); _Pragma("unroll") for (int m = 0; m < 4; ++m) _Pragma("unroll") for (int n = 0; n < 2; ++n) _Pragma("unroll") for (int k = 0; k < 2; ++k) \
;       acc[ai][bj][m][n] = __builtin_amdgcn_mfma_f32_16x16x32_bf16(Bt_[n][k], At[m][k], acc[ai][bj][m][n], 0, 0, 0); \
;     __builtin_amdgcn_s_setprio(0); } while (0)
; #define WAIT_V(n) asm volatile("s_waitcnt vmcnt(" #n ")" ::: "memory")
; #define WAIT_L(n) asm volatile("s_waitcnt lgkmcnt(" #n ")" ::: "memory")
; #define BAR __builtin_amdgcn_s_barrier()
; #define SCHED __builtin_amdgcn_sched_barrier(0)
; template <int MODE>
; DEV void gemm_phase(const bf16_t* __restrict__ A, const bf16_t* __restrict__ Bt, int M, int N, int K, bf16_t* __restrict__ Out, int ldo,
;                     const float* __restrict__ rstd, const float* __restrict__ rope) {
;     ...
;       LDB(B0, 0, 0); LDB(B1, 0, 1); SCHED; LDA(At, 0, 0); STAGE_A(SA(1, 1), a1 + hstep);
;       WAIT_V(8); WAIT_L(0); BAR; MMA(0, 0, At, B0); MMA(0, 1, At, B1); BAR; SCHED;
;       LDA(At, 0, 1); STAGE_B(SB_(0, 0), b2); STAGE_B(SB_(0, 1), b2 + hstep); STAGE_A(SA(0, 0), a2);
;       WAIT_V(8); WAIT_L(0); BAR; MMA(1, 0, At, B0); MMA(1, 1, At, B1); BAR; SCHED;
;       LDB(B0, 1, 0); LDB(B1, 1, 1); SCHED; LDA(At, 1, 0); STAGE_A(SA(0, 1), a2 + hstep);
;       WAIT_V(8); WAIT_L(0); BAR; MMA(0, 0, At, B0); MMA(0, 1, At, B1); BAR; SCHED;
;       LDA(At, 1, 1); STAGE_B(SB_(1, 0), b3); STAGE_B(SB_(1, 1), b3 + hstep); STAGE_A(SA(1, 0), a3);
;       WAIT_V(8); WAIT_L(0); BAR; MMA(1, 0, At, B0); MMA(1, 1, At, B1); BAR; SCHED;
	v_mfma_f32_16x16x32_bf16 v[60:63], v[144:147], v[176:179], v[60:63]
	v_mfma_f32_16x16x32_bf16 v[56:59], v[152:155], v[176:179], v[56:59]
	v_mfma_f32_16x16x32_bf16 v[52:55], v[144:147], v[184:187], v[52:55]
	v_mfma_f32_16x16x32_bf16 v[48:51], v[152:155], v[184:187], v[48:51]
	v_mfma_f32_16x16x32_bf16 v[36:39], v[144:147], v[194:197], v[36:39]
	v_mfma_f32_16x16x32_bf16 v[32:35], v[152:155], v[194:197], v[32:35]
	v_mfma_f32_16x16x32_bf16 v[20:23], v[144:147], v[202:205], v[20:23]
	v_mfma_f32_16x16x32_bf16 v[16:19], v[152:155], v[202:205], v[16:19]
	v_mfma_f32_16x16x32_bf16 v[60:63], v[148:151], v[180:183], v[60:63]
	v_mfma_f32_16x16x32_bf16 v[56:59], v[156:159], v[180:183], v[56:59]
	v_mfma_f32_16x16x32_bf16 v[52:55], v[148:151], v[188:191], v[52:55]
	v_mfma_f32_16x16x32_bf16 v[48:51], v[156:159], v[188:191], v[48:51]
	v_mfma_f32_16x16x32_bf16 v[36:39], v[148:151], v[198:201], v[36:39]
	v_mfma_f32_16x16x32_bf16 v[32:35], v[156:159], v[198:201], v[32:35]
	v_mfma_f32_16x16x32_bf16 v[20:23], v[148:151], v[206:209], v[20:23]
	v_mfma_f32_16x16x32_bf16 v[16:19], v[156:159], v[206:209], v[16:19]
	s_setprio 0
	s_setprio 1
	v_mfma_f32_16x16x32_bf16 v[44:47], v[160:163], v[176:179], v[44:47]
	v_mfma_f32_16x16x32_bf16 v[40:43], v[168:171], v[176:179], v[40:43]
	v_mfma_f32_16x16x32_bf16 v[28:31], v[160:163], v[184:187], v[28:31]
	v_mfma_f32_16x16x32_bf16 v[24:27], v[168:171], v[184:187], v[24:27]
	v_mfma_f32_16x16x32_bf16 v[12:15], v[160:163], v[194:197], v[12:15]
	v_mfma_f32_16x16x32_bf16 v[8:11], v[168:171], v[194:197], v[8:11]
	v_mfma_f32_16x16x32_bf16 v[4:7], v[160:163], v[202:205], v[4:7]
	v_mfma_f32_16x16x32_bf16 v[0:3], v[168:171], v[202:205], v[0:3]
	v_mfma_f32_16x16x32_bf16 v[44:47], v[164:167], v[180:183], v[44:47]
	v_mfma_f32_16x16x32_bf16 v[40:43], v[172:175], v[180:183], v[40:43]
	v_mfma_f32_16x16x32_bf16 v[28:31], v[164:167], v[188:191], v[28:31]
	v_mfma_f32_16x16x32_bf16 v[24:27], v[172:175], v[188:191], v[24:27]
	v_mfma_f32_16x16x32_bf16 v[12:15], v[164:167], v[198:201], v[12:15]
	v_mfma_f32_16x16x32_bf16 v[8:11], v[172:175], v[198:201], v[8:11]
	v_mfma_f32_16x16x32_bf16 v[4:7], v[164:167], v[206:209], v[4:7]
	v_mfma_f32_16x16x32_bf16 v[0:3], v[172:175], v[206:209], v[0:3]
	s_barrier
	s_setprio 0
	s_add_i32 s39, 0, 0x18000
	v_add_u32_e32 v143, s39, v141
	s_add_i32 s40, 0, 0x1c000
	ds_read_b128 v[144:147], v143
	ds_read_b128 v[148:151], v143 offset:1024
	ds_read_b128 v[152:155], v143 offset:2048
	ds_read_b128 v[156:159], v143 offset:3072
	v_add_u32_e32 v143, s40, v141
	ds_read_b128 v[160:163], v143
	ds_read_b128 v[164:167], v143 offset:1024
	ds_read_b128 v[168:171], v143 offset:2048
	ds_read_b128 v[172:175], v143 offset:3072
	s_add_u32 s22, s22, 0x80000
	s_addc_u32 s23, s23, 0
	s_mov_b32 m0, s27
	v_lshl_add_u64 v[226:227], s[22:23], 0, v[132:133]
	ds_read_b128 v[176:179], v142 offset:32768
	ds_read_b128 v[180:183], v142 offset:33792
	ds_read_b128 v[184:187], v142 offset:34816
	ds_read_b128 v[188:191], v142 offset:35840
	ds_read_b128 v[194:197], v142 offset:36864
	ds_read_b128 v[198:201], v142 offset:37888
	ds_read_b128 v[202:205], v142 offset:38912
	ds_read_b128 v[206:209], v142 offset:39936
	global_load_lds_dwordx4 v[226:227], off
	v_lshl_add_u64 v[226:227], s[22:23], 0, v[130:131]
	s_mov_b32 m0, s28
	s_nop 0
	global_load_lds_dwordx4 v[226:227], off
	s_waitcnt vmcnt(8)
	s_waitcnt lgkmcnt(0)
	s_setprio 1
	s_barrier
	v_mfma_f32_16x16x32_bf16 v[124:127], v[144:147], v[176:179], v[124:127]
	v_mfma_f32_16x16x32_bf16 v[120:123], v[152:155], v[176:179], v[120:123]
	v_mfma_f32_16x16x32_bf16 v[116:119], v[144:147], v[184:187], v[116:119]
	v_mfma_f32_16x16x32_bf16 v[112:115], v[152:155], v[184:187], v[112:115]
	v_mfma_f32_16x16x32_bf16 v[100:103], v[144:147], v[194:197], v[100:103]
	v_mfma_f32_16x16x32_bf16 v[96:99], v[152:155], v[194:197], v[96:99]
	v_mfma_f32_16x16x32_bf16 v[84:87], v[144:147], v[202:205], v[84:87]
	v_mfma_f32_16x16x32_bf16 v[80:83], v[152:155], v[202:205], v[80:83]
	v_mfma_f32_16x16x32_bf16 v[124:127], v[148:151], v[180:183], v[124:127]
	v_mfma_f32_16x16x32_bf16 v[120:123], v[156:159], v[180:183], v[120:123]
	v_mfma_f32_16x16x32_bf16 v[116:119], v[148:151], v[188:191], v[116:119]
	v_mfma_f32_16x16x32_bf16 v[112:115], v[156:159], v[188:191], v[112:115]
	v_mfma_f32_16x16x32_bf16 v[100:103], v[148:151], v[198:201], v[100:103]
	v_mfma_f32_16x16x32_bf16 v[96:99], v[156:159], v[198:201], v[96:99]
	v_mfma_f32_16x16x32_bf16 v[84:87], v[148:151], v[206:209], v[84:87]
	v_mfma_f32_16x16x32_bf16 v[80:83], v[156:159], v[206:209], v[80:83]
	s_setprio 0
	s_setprio 1
	v_mfma_f32_16x16x32_bf16 v[108:111], v[160:163], v[176:179], v[108:111]
	v_mfma_f32_16x16x32_bf16 v[104:107], v[168:171], v[176:179], v[104:107]
	v_mfma_f32_16x16x32_bf16 v[92:95], v[160:163], v[184:187], v[92:95]
	v_mfma_f32_16x16x32_bf16 v[88:91], v[168:171], v[184:187], v[88:91]
	v_mfma_f32_16x16x32_bf16 v[76:79], v[160:163], v[194:197], v[76:79]
	v_mfma_f32_16x16x32_bf16 v[72:75], v[168:171], v[194:197], v[72:75]
	v_mfma_f32_16x16x32_bf16 v[68:71], v[160:163], v[202:205], v[68:71]
	v_mfma_f32_16x16x32_bf16 v[64:67], v[168:171], v[202:205], v[64:67]
	v_mfma_f32_16x16x32_bf16 v[108:111], v[164:167], v[180:183], v[108:111]
	v_mfma_f32_16x16x32_bf16 v[104:107], v[172:175], v[180:183], v[104:107]
	v_mfma_f32_16x16x32_bf16 v[92:95], v[164:167], v[188:191], v[92:95]
	v_mfma_f32_16x16x32_bf16 v[88:91], v[172:175], v[188:191], v[88:91]
	v_mfma_f32_16x16x32_bf16 v[76:79], v[164:167], v[198:201], v[76:79]
	v_mfma_f32_16x16x32_bf16 v[72:75], v[172:175], v[198:201], v[72:75]
	v_mfma_f32_16x16x32_bf16 v[68:71], v[164:167], v[206:209], v[68:71]
	v_mfma_f32_16x16x32_bf16 v[64:67], v[172:175], v[206:209], v[64:67]
	s_barrier
; #define STAGE_A(bufoff, gbase) STAGEX(bufoff, gbase, voffA)
; #define STAGE_B(bufoff, gbase) STAGEX(bufoff, gbase, voffB)
; #define LDA(dst, b, h) do { _Pragma("unroll") for (int m = 0; m < 4; ++m) _Pragma("unroll") for (int k = 0; k < 2; ++k) dst[m][k] = *(const __attribute__((address_space(3))) bf16x8*)(lds + SA(b, h) + aoff + m * 2048 + k * 1024); } while (0)
; #define LDB(dst, b, h) do { _Pragma("unroll") for (int n = 0; n < 2; ++n) _Pragma("unroll") for (int k = 0; k < 2; ++k) dst[n][k] = *(const __attribute__((address_space(3))) bf16x8*)(lds + SB_(b, h) + boff + n * 2048 + k * 1024); } while (0)
; #define MMA(ai, bj, At, Bt_) do { __builtin_amdgcn_s_setprio(1); _Pragma("unroll") for (int m = 0; m < 4; ++m) _Pragma("unroll") for (int n = 0; n < 2; ++n) _Pragma("unroll") for (int k = 0; k < 2; ++k) \
;       acc[ai][bj][m][n] = __builtin_amdgcn_mfma_f32_16x16x32_bf16(Bt_[n][k], At[m][k], acc[ai][bj][m][n], 0, 0, 0); \
;     __builtin_amdgcn_s_setprio(0); } while (0)
; #define WAIT_V(n) asm volatile("s_waitcnt vmcnt(" #n ")" ::: "memory")
; #define WAIT_L(n) asm volatile("s_waitcnt lgkmcnt(" #n ")" ::: "memory")
; #define BAR __builtin_amdgcn_s_barrier()
; #define SCHED __builtin_amdgcn_sched_barrier(0)
; template <int MODE>
; DEV void gemm_phase(const bf16_t* __restrict__ A, const bf16_t* __restrict__ Bt, int M, int N, int K, bf16_t* __restrict__ Out, int ldo,
;                     const float* __restrict__ rstd, const float* __restrict__ rope) {
;     ...
;       LDA(At, 0, 1); STAGE_B(SB_(0, 0), b2); STAGE_B(SB_(0, 1), b2 + hstep); STAGE_A(SA(0, 0), a2);
;       WAIT_V(8); WAIT_L(0); BAR; MMA(1, 0, At, B0); MMA(1, 1, At, B1); BAR; SCHED;
;       LDB(B0, 1, 0); LDB(B1, 1, 1); SCHED; LDA(At, 1, 0); STAGE_A(SA(0, 1), a2 + hstep);
;       WAIT_V(8); WAIT_L(0); BAR; MMA(0, 0, At, B0); MMA(0, 1, At, B1); BAR; SCHED;
;       LDA(At, 1, 1); STAGE_B(SB_(1, 0), b3); STAGE_B(SB_(1, 1), b3 + hstep); STAGE_A(SA(1, 0), a3);
;       WAIT_V(8); WAIT_L(0); BAR; MMA(1, 0, At, B0); MMA(1, 1, At, B1); BAR; SCHED;
;     }
;     if (wr == 0) BAR;
	s_setprio 0
	s_add_i32 s22, s39, s24
	v_lshl_add_u64 v[212:213], v[212:213], 0, s[44:45]
	s_mov_b32 m0, s22
	ds_read_b128 v[176:179], v142 offset:49152
	ds_read_b128 v[180:183], v142 offset:50176
	ds_read_b128 v[184:187], v142 offset:51200
	ds_read_b128 v[188:191], v142 offset:52224
	ds_read_b128 v[194:197], v142 offset:53248
	ds_read_b128 v[198:201], v142 offset:54272
	ds_read_b128 v[202:205], v142 offset:55296
	ds_read_b128 v[206:209], v142 offset:56320
	global_load_lds_dwordx4 v[212:213], off
	s_add_i32 m0, s22, 0x2000
	s_add_u32 s20, s20, 0x80080
	v_lshl_add_u64 v[212:213], v[214:215], 0, s[44:45]
	s_addc_u32 s21, s21, 0
	s_add_i32 s22, s40, s24
	global_load_lds_dwordx4 v[212:213], off
	v_lshl_add_u64 v[212:213], s[20:21], 0, v[192:193]
	s_mov_b32 m0, s22
	s_nop 0
	global_load_lds_dwordx4 v[212:213], off
	v_lshl_add_u64 v[212:213], s[20:21], 0, v[128:129]
	s_add_i32 m0, s22, 0x2000
	s_nop 0
	global_load_lds_dwordx4 v[212:213], off
	v_lshl_add_u64 v[212:213], v[222:223], 0, s[44:45]
	s_mov_b32 m0, s29
	s_nop 0
	global_load_lds_dwordx4 v[212:213], off
	v_lshl_add_u64 v[212:213], v[224:225], 0, s[44:45]
	s_mov_b32 m0, s30
	s_nop 0
	global_load_lds_dwordx4 v[212:213], off
	s_waitcnt vmcnt(8)
	s_waitcnt lgkmcnt(0)
	s_setprio 1
	s_barrier
	v_mfma_f32_16x16x32_bf16 v[60:63], v[144:147], v[176:179], v[60:63]
	v_mfma_f32_16x16x32_bf16 v[56:59], v[152:155], v[176:179], v[56:59]
	v_mfma_f32_16x16x32_bf16 v[52:55], v[144:147], v[184:187], v[52:55]
	v_mfma_f32_16x16x32_bf16 v[48:51], v[152:155], v[184:187], v[48:51]
	v_mfma_f32_16x16x32_bf16 v[36:39], v[144:147], v[194:197], v[36:39]
	v_mfma_f32_16x16x32_bf16 v[32:35], v[152:155], v[194:197], v[32:35]
	v_mfma_f32_16x16x32_bf16 v[20:23], v[144:147], v[202:205], v[20:23]
	v_mfma_f32_16x16x32_bf16 v[16:19], v[152:155], v[202:205], v[16:19]
	v_mfma_f32_16x16x32_bf16 v[60:63], v[148:151], v[180:183], v[60:63]
	v_mfma_f32_16x16x32_bf16 v[56:59], v[156:159], v[180:183], v[56:59]
	v_mfma_f32_16x16x32_bf16 v[52:55], v[148:151], v[188:191], v[52:55]
	v_mfma_f32_16x16x32_bf16 v[48:51], v[156:159], v[188:191], v[48:51]
	v_mfma_f32_16x16x32_bf16 v[36:39], v[148:151], v[198:201], v[36:39]
	v_mfma_f32_16x16x32_bf16 v[32:35], v[156:159], v[198:201], v[32:35]
	v_mfma_f32_16x16x32_bf16 v[20:23], v[148:151], v[206:209], v[20:23]
	v_mfma_f32_16x16x32_bf16 v[16:19], v[156:159], v[206:209], v[16:19]
	s_setprio 0
	s_setprio 1
	v_mfma_f32_16x16x32_bf16 v[44:47], v[160:163], v[176:179], v[44:47]
	v_mfma_f32_16x16x32_bf16 v[40:43], v[168:171], v[176:179], v[40:43]
	v_mfma_f32_16x16x32_bf16 v[28:31], v[160:163], v[184:187], v[28:31]
	v_mfma_f32_16x16x32_bf16 v[24:27], v[168:171], v[184:187], v[24:27]
	v_mfma_f32_16x16x32_bf16 v[12:15], v[160:163], v[194:197], v[12:15]
	v_mfma_f32_16x16x32_bf16 v[8:11], v[168:171], v[194:197], v[8:11]
	v_mfma_f32_16x16x32_bf16 v[4:7], v[160:163], v[202:205], v[4:7]
	v_mfma_f32_16x16x32_bf16 v[0:3], v[168:171], v[202:205], v[0:3]
	v_mfma_f32_16x16x32_bf16 v[44:47], v[164:167], v[180:183], v[44:47]
	v_mfma_f32_16x16x32_bf16 v[40:43], v[172:175], v[180:183], v[40:43]
	v_mfma_f32_16x16x32_bf16 v[28:31], v[164:167], v[188:191], v[28:31]
	v_mfma_f32_16x16x32_bf16 v[24:27], v[172:175], v[188:191], v[24:27]
	v_mfma_f32_16x16x32_bf16 v[12:15], v[164:167], v[198:201], v[12:15]
	v_mfma_f32_16x16x32_bf16 v[8:11], v[172:175], v[198:201], v[8:11]
	v_mfma_f32_16x16x32_bf16 v[4:7], v[164:167], v[206:209], v[4:7]
	v_mfma_f32_16x16x32_bf16 v[0:3], v[172:175], v[206:209], v[0:3]
	s_barrier
	s_setprio 0
	s_add_i32 s38, s38, 2
	s_add_u32 s18, s18, 0x100
	s_addc_u32 s19, s19, 0
	s_add_u32 s36, s36, 0x100
	s_addc_u32 s37, s37, 0
	s_cmp_gt_u32 s38, 29
	s_cbranch_scc0 .LBB0_493
	s_and_b64 vcc, exec, s[6:7]
	s_cbranch_vccz .LBB0_496
	s_barrier

; #define STAGE_A(bufoff, gbase) STAGEX(bufoff, gbase, voffA)
; #define STAGE_B(bufoff, gbase) STAGEX(bufoff, gbase, voffB)
; #define LDA(dst, b, h) do { _Pragma("unroll") for (int m = 0; m < 4; ++m) _Pragma("unroll") for (int k = 0; k < 2; ++k) dst[m][k] = *(const __attribute__((address_space(3))) bf16x8*)(lds + SA(b, h) + aoff + m * 2048 + k * 1024); } while (0)
; #define LDB(dst, b, h) do { _Pragma("unroll") for (int n = 0; n < 2; ++n) _Pragma("unroll") for (int k = 0; k < 2; ++k) dst[n][k] = *(const __attribute__((address_space(3))) bf16x8*)(lds + SB_(b, h) + boff + n * 2048 + k * 1024); } while (0)
; #define MMA(ai, bj, At, Bt_) do { __builtin_amdgcn_s_setprio(1); _Pragma("unroll") for (int m = 0; m < 4; ++m) _Pragma("unroll") for (int n = 0; n < 2; ++n) _Pragma("unroll") for (int k = 0; k < 2; ++k) \
;       acc[ai][bj][m][n] = __builtin_amdgcn_mfma_f32_16x16x32_bf16(Bt_[n][k], At[m][k], acc[ai][bj][m][n], 0, 0, 0); \
;     __builtin_amdgcn_s_setprio(0); } while (0)
; #define WAIT_V(n) asm volatile("s_waitcnt vmcnt(" #n ")" ::: "memory")
; #define WAIT_L(n) asm volatile("s_waitcnt lgkmcnt(" #n ")" ::: "memory")
; #define BAR __builtin_amdgcn_s_barrier()
; #define SCHED __builtin_amdgcn_sched_barrier(0)
; template <int MODE>
; DEV void gemm_phase(const bf16_t* __restrict__ A, const bf16_t* __restrict__ Bt, int M, int N, int K, bf16_t* __restrict__ Out, int ldo,
;                     const float* __restrict__ rstd, const float* __restrict__ rope) {
;     ...
;     for (int t = 0; t < nt; t += 2) {
;       const bool last = (t == nt - 2);
;       const char* a1 = cA + (size_t)(t + 1) * 128;
;       const char* a2 = last ? nA : cA + (size_t)(t + 2) * 128; const char* b2 = last ? nB : cB + (size_t)(t + 2) * 128;
;       const char* a3 = a2 + 128; const char* b3 = b2 + 128;
;       LDB(B0, 0, 0); LDB(B1, 0, 1); SCHED; LDA(At, 0, 0); STAGE_A(SA(1, 1), a1 + hstep);
;       WAIT_V(8); WAIT_L(0); BAR; MMA(0, 0, At, B0); MMA(0, 1, At, B1); BAR; SCHED;
;       LDA(At, 0, 1); STAGE_B(SB_(0, 0), b2); STAGE_B(SB_(0, 1), b2 + hstep); STAGE_A(SA(0, 0), a2);
;       WAIT_V(8); WAIT_L(0); BAR; MMA(1, 0, At, B0); MMA(1, 1, At, B1); BAR; SCHED;
.LBB0_618:
	s_add_u32 s20, s38, s18
	s_addc_u32 s21, s39, s19
	s_add_u32 s20, s20, 0x12200100
	s_addc_u32 s21, s21, 0
	s_add_u32 s43, s40, s18
	s_addc_u32 s44, s41, s19
	s_add_i32 s45, 0, 0x10000
	s_cmpk_eq_i32 s18, 0xf00
	s_cselect_b32 s23, s36, s21
	s_cselect_b32 s22, s9, s20
	v_add_u32_e32 v147, s45, v145
	s_cselect_b32 s21, s37, s44
	s_cselect_b32 s20, s11, s43
	s_add_i32 s43, 0, 0x14000
	ds_read_b128 v[148:151], v147
	ds_read_b128 v[152:155], v147 offset:1024
	ds_read_b128 v[156:159], v147 offset:2048
	ds_read_b128 v[160:163], v147 offset:3072
	v_add_u32_e32 v147, s43, v145
	ds_read_b128 v[164:167], v147
	ds_read_b128 v[168:171], v147 offset:1024
	ds_read_b128 v[172:175], v147 offset:2048
	ds_read_b128 v[176:179], v147 offset:3072
	v_lshl_add_u64 v[222:223], v[140:141], 0, s[18:19]
	s_add_i32 m0, s25, 0xc000
	ds_read_b128 v[180:183], v146
	ds_read_b128 v[184:187], v146 offset:1024
	ds_read_b128 v[188:191], v146 offset:2048
	ds_read_b128 v[194:197], v146 offset:3072
	ds_read_b128 v[198:201], v146 offset:4096
	ds_read_b128 v[202:205], v146 offset:5120
	ds_read_b128 v[206:209], v146 offset:6144
	ds_read_b128 v[212:215], v146 offset:7168
	global_load_lds_dwordx4 v[222:223], off
	v_lshl_add_u64 v[222:223], v[142:143], 0, s[18:19]
	s_add_i32 m0, s25, 0xe000
	s_nop 0
	global_load_lds_dwordx4 v[222:223], off
	s_waitcnt vmcnt(8)
	s_waitcnt lgkmcnt(0)
	s_setprio 1
	s_barrier
	v_mfma_f32_16x16x32_bf16 v[124:127], v[148:151], v[180:183], v[124:127]
	v_mfma_f32_16x16x32_bf16 v[120:123], v[156:159], v[180:183], v[120:123]
	v_mfma_f32_16x16x32_bf16 v[108:111], v[148:151], v[188:191], v[108:111]
	v_mfma_f32_16x16x32_bf16 v[104:107], v[156:159], v[188:191], v[104:107]
	v_mfma_f32_16x16x32_bf16 v[92:95], v[148:151], v[198:201], v[92:95]
	v_mfma_f32_16x16x32_bf16 v[88:91], v[156:159], v[198:201], v[88:91]
	v_mfma_f32_16x16x32_bf16 v[76:79], v[148:151], v[206:209], v[76:79]
	v_mfma_f32_16x16x32_bf16 v[72:75], v[156:159], v[206:209], v[72:75]
	v_mfma_f32_16x16x32_bf16 v[124:127], v[152:155], v[184:187], v[124:127]
	v_mfma_f32_16x16x32_bf16 v[120:123], v[160:163], v[184:187], v[120:123]
	v_mfma_f32_16x16x32_bf16 v[108:111], v[152:155], v[194:197], v[108:111]
	v_mfma_f32_16x16x32_bf16 v[104:107], v[160:163], v[194:197], v[104:107]
	v_mfma_f32_16x16x32_bf16 v[92:95], v[152:155], v[202:205], v[92:95]
	v_mfma_f32_16x16x32_bf16 v[88:91], v[160:163], v[202:205], v[88:91]
	v_mfma_f32_16x16x32_bf16 v[76:79], v[152:155], v[212:215], v[76:79]
	v_mfma_f32_16x16x32_bf16 v[72:75], v[160:163], v[212:215], v[72:75]
	s_setprio 0
	s_setprio 1
	v_mfma_f32_16x16x32_bf16 v[116:119], v[164:167], v[180:183], v[116:119]
	v_mfma_f32_16x16x32_bf16 v[112:115], v[172:175], v[180:183], v[112:115]
	v_mfma_f32_16x16x32_bf16 v[100:103], v[164:167], v[188:191], v[100:103]
	v_mfma_f32_16x16x32_bf16 v[96:99], v[172:175], v[188:191], v[96:99]
	v_mfma_f32_16x16x32_bf16 v[84:87], v[164:167], v[198:201], v[84:87]
	v_mfma_f32_16x16x32_bf16 v[80:83], v[172:175], v[198:201], v[80:83]
	v_mfma_f32_16x16x32_bf16 v[68:71], v[164:167], v[206:209], v[68:71]
	v_mfma_f32_16x16x32_bf16 v[64:67], v[172:175], v[206:209], v[64:67]
	v_mfma_f32_16x16x32_bf16 v[116:119], v[168:171], v[184:187], v[116:119]
	v_mfma_f32_16x16x32_bf16 v[112:115], v[176:179], v[184:187], v[112:115]
	v_mfma_f32_16x16x32_bf16 v[100:103], v[168:171], v[194:197], v[100:103]
	v_mfma_f32_16x16x32_bf16 v[96:99], v[176:179], v[194:197], v[96:99]
	v_mfma_f32_16x16x32_bf16 v[84:87], v[168:171], v[202:205], v[84:87]
	v_mfma_f32_16x16x32_bf16 v[80:83], v[176:179], v[202:205], v[80:83]
	v_mfma_f32_16x16x32_bf16 v[68:71], v[168:171], v[212:215], v[68:71]
	v_mfma_f32_16x16x32_bf16 v[64:67], v[176:179], v[212:215], v[64:67]
	s_barrier
	s_setprio 0
	s_add_i32 s44, s45, s24
	v_lshl_add_u64 v[222:223], s[20:21], 0, v[192:193]
	s_mov_b32 m0, s44
	ds_read_b128 v[180:183], v146 offset:16384
	ds_read_b128 v[184:187], v146 offset:17408
	ds_read_b128 v[188:191], v146 offset:18432
	ds_read_b128 v[194:197], v146 offset:19456
	ds_read_b128 v[198:201], v146 offset:20480
	ds_read_b128 v[202:205], v146 offset:21504
	ds_read_b128 v[206:209], v146 offset:22528
	ds_read_b128 v[212:215], v146 offset:23552
	global_load_lds_dwordx4 v[222:223], off
	s_add_i32 m0, s44, 0x2000
	s_add_u32 s44, s20, 0x80000
	v_lshl_add_u64 v[224:225], s[20:21], 0, v[128:129]
	s_addc_u32 s45, s21, 0
	s_add_i32 s43, s43, s24
	global_load_lds_dwordx4 v[224:225], off
	v_lshl_add_u64 v[226:227], s[44:45], 0, v[192:193]
	s_mov_b32 m0, s43
	v_lshl_add_u64 v[228:229], s[22:23], 0, v[130:131]
	global_load_lds_dwordx4 v[226:227], off
	v_lshl_add_u64 v[226:227], s[44:45], 0, v[128:129]
	s_add_i32 m0, s43, 0x2000
	s_nop 0
	global_load_lds_dwordx4 v[226:227], off
	v_lshl_add_u64 v[226:227], s[22:23], 0, v[132:133]
	s_mov_b32 m0, s25
	s_nop 0
	global_load_lds_dwordx4 v[226:227], off
	s_mov_b32 m0, s26
	s_nop 0
	global_load_lds_dwordx4 v[228:229], off
	s_waitcnt vmcnt(8)
	s_waitcnt lgkmcnt(0)
	s_setprio 1
	s_barrier
; #define STAGE_A(bufoff, gbase) STAGEX(bufoff, gbase, voffA)
; #define STAGE_B(bufoff, gbase) STAGEX(bufoff, gbase, voffB)
; #define LDA(dst, b, h) do { _Pragma("unroll") for (int m = 0; m < 4; ++m) _Pragma("unroll") for (int k = 0; k < 2; ++k) dst[m][k] = *(const __attribute__((address_space(3))) bf16x8*)(lds + SA(b, h) + aoff + m * 2048 + k * 1024); } while (0)
; #define LDB(dst, b, h) do { _Pragma("unroll") for (int n = 0; n < 2; ++n) _Pragma("unroll") for (int k = 0; k < 2; ++k) dst[n][k] = *(const __attribute__((address_space(3))) bf16x8*)(lds + SB_(b, h) + boff + n * 2048 + k * 1024); } while (0)
; #define MMA(ai, bj, At, Bt_) do { __builtin_amdgcn_s_setprio(1); _Pragma("unroll") for (int m = 0; m < 4; ++m) _Pragma("unroll") for (int n = 0; n < 2; ++n) _Pragma("unroll") for (int k = 0; k < 2; ++k) \
;       acc[ai][bj][m][n] = __builtin_amdgcn_mfma_f32_16x16x32_bf16(Bt_[n][k], At[m][k], acc[ai][bj][m][n], 0, 0, 0); \
;     __builtin_amdgcn_s_setprio(0); } while (0)
; #define WAIT_V(n) asm volatile("s_waitcnt vmcnt(" #n ")" ::: "memory")
; #define WAIT_L(n) asm volatile("s_waitcnt lgkmcnt(" #n ")" ::: "memory")
; #define BAR __builtin_amdgcn_s_barrier()
; #define SCHED __builtin_amdgcn_sched_barrier(0)
; template <int MODE>
; DEV void gemm_phase(const bf16_t* __restrict__ A, const bf16_t* __restrict__ Bt, int M, int N, int K, bf16_t* __restrict__ Out, int ldo,
;                     const float* __restrict__ rstd, const float* __restrict__ rope) {
;     ...
;       LDB(B0, 0, 0); LDB(B1, 0, 1); SCHED; LDA(At, 0, 0); STAGE_A(SA(1, 1), a1 + hstep);
;       WAIT_V(8); WAIT_L(0); BAR; MMA(0, 0, At, B0); MMA(0, 1, At, B1); BAR; SCHED;
;       LDA(At, 0, 1); STAGE_B(SB_(0, 0), b2); STAGE_B(SB_(0, 1), b2 + hstep); STAGE_A(SA(0, 0), a2);
;       WAIT_V(8); WAIT_L(0); BAR; MMA(1, 0, At, B0); MMA(1, 1, At, B1); BAR; SCHED;
;       LDB(B0, 1, 0); LDB(B1, 1, 1); SCHED; LDA(At, 1, 0); STAGE_A(SA(0, 1), a2 + hstep);
;       WAIT_V(8); WAIT_L(0); BAR; MMA(0, 0, At, B0); MMA(0, 1, At, B1); BAR; SCHED;
;       LDA(At, 1, 1); STAGE_B(SB_(1, 0), b3); STAGE_B(SB_(1, 1), b3 + hstep); STAGE_A(SA(1, 0), a3);
;       WAIT_V(8); WAIT_L(0); BAR; MMA(1, 0, At, B0); MMA(1, 1, At, B1); BAR; SCHED;
	v_mfma_f32_16x16x32_bf16 v[60:63], v[148:151], v[180:183], v[60:63]
	v_mfma_f32_16x16x32_bf16 v[56:59], v[156:159], v[180:183], v[56:59]
	v_mfma_f32_16x16x32_bf16 v[44:47], v[148:151], v[188:191], v[44:47]
	v_mfma_f32_16x16x32_bf16 v[40:43], v[156:159], v[188:191], v[40:43]
	v_mfma_f32_16x16x32_bf16 v[28:31], v[148:151], v[198:201], v[28:31]
	v_mfma_f32_16x16x32_bf16 v[24:27], v[156:159], v[198:201], v[24:27]
	v_mfma_f32_16x16x32_bf16 v[12:15], v[148:151], v[206:209], v[12:15]
	v_mfma_f32_16x16x32_bf16 v[4:7], v[156:159], v[206:209], v[4:7]
	v_mfma_f32_16x16x32_bf16 v[60:63], v[152:155], v[184:187], v[60:63]
	v_mfma_f32_16x16x32_bf16 v[56:59], v[160:163], v[184:187], v[56:59]
	v_mfma_f32_16x16x32_bf16 v[44:47], v[152:155], v[194:197], v[44:47]
	v_mfma_f32_16x16x32_bf16 v[40:43], v[160:163], v[194:197], v[40:43]
	v_mfma_f32_16x16x32_bf16 v[28:31], v[152:155], v[202:205], v[28:31]
	v_mfma_f32_16x16x32_bf16 v[24:27], v[160:163], v[202:205], v[24:27]
	v_mfma_f32_16x16x32_bf16 v[12:15], v[152:155], v[212:215], v[12:15]
	v_mfma_f32_16x16x32_bf16 v[4:7], v[160:163], v[212:215], v[4:7]
	s_setprio 0
	s_setprio 1
	v_mfma_f32_16x16x32_bf16 v[52:55], v[164:167], v[180:183], v[52:55]
	v_mfma_f32_16x16x32_bf16 v[48:51], v[172:175], v[180:183], v[48:51]
	v_mfma_f32_16x16x32_bf16 v[36:39], v[164:167], v[188:191], v[36:39]
	v_mfma_f32_16x16x32_bf16 v[32:35], v[172:175], v[188:191], v[32:35]
	v_mfma_f32_16x16x32_bf16 v[20:23], v[164:167], v[198:201], v[20:23]
	v_mfma_f32_16x16x32_bf16 v[16:19], v[172:175], v[198:201], v[16:19]
	v_mfma_f32_16x16x32_bf16 v[8:11], v[164:167], v[206:209], v[8:11]
	v_mfma_f32_16x16x32_bf16 v[0:3], v[172:175], v[206:209], v[0:3]
	v_mfma_f32_16x16x32_bf16 v[52:55], v[168:171], v[184:187], v[52:55]
	v_mfma_f32_16x16x32_bf16 v[48:51], v[176:179], v[184:187], v[48:51]
	v_mfma_f32_16x16x32_bf16 v[36:39], v[168:171], v[194:197], v[36:39]
	v_mfma_f32_16x16x32_bf16 v[32:35], v[176:179], v[194:197], v[32:35]
	v_mfma_f32_16x16x32_bf16 v[20:23], v[168:171], v[202:205], v[20:23]
	v_mfma_f32_16x16x32_bf16 v[16:19], v[176:179], v[202:205], v[16:19]
	v_mfma_f32_16x16x32_bf16 v[8:11], v[168:171], v[212:215], v[8:11]
	v_mfma_f32_16x16x32_bf16 v[0:3], v[176:179], v[212:215], v[0:3]
	s_barrier
	s_setprio 0
	s_add_i32 s43, 0, 0x18000
	v_add_u32_e32 v147, s43, v145
	s_add_i32 s44, 0, 0x1c000
	ds_read_b128 v[148:151], v147
	ds_read_b128 v[152:155], v147 offset:1024
	ds_read_b128 v[156:159], v147 offset:2048
	ds_read_b128 v[160:163], v147 offset:3072
	v_add_u32_e32 v147, s44, v145
	ds_read_b128 v[164:167], v147
	ds_read_b128 v[168:171], v147 offset:1024
	ds_read_b128 v[172:175], v147 offset:2048
	ds_read_b128 v[176:179], v147 offset:3072
	s_add_u32 s22, s22, 0x80000
	s_addc_u32 s23, s23, 0
	s_mov_b32 m0, s27
	v_lshl_add_u64 v[230:231], s[22:23], 0, v[132:133]
	ds_read_b128 v[180:183], v146 offset:32768
	ds_read_b128 v[184:187], v146 offset:33792
	ds_read_b128 v[188:191], v146 offset:34816
	ds_read_b128 v[194:197], v146 offset:35840
	ds_read_b128 v[198:201], v146 offset:36864
	ds_read_b128 v[202:205], v146 offset:37888
	ds_read_b128 v[206:209], v146 offset:38912
	ds_read_b128 v[212:215], v146 offset:39936
	global_load_lds_dwordx4 v[230:231], off
	v_lshl_add_u64 v[230:231], s[22:23], 0, v[130:131]
	s_mov_b32 m0, s28
	s_nop 0
	global_load_lds_dwordx4 v[230:231], off
	s_waitcnt vmcnt(8)
	s_waitcnt lgkmcnt(0)
	s_setprio 1
	s_barrier
	v_mfma_f32_16x16x32_bf16 v[124:127], v[148:151], v[180:183], v[124:127]
	v_mfma_f32_16x16x32_bf16 v[120:123], v[156:159], v[180:183], v[120:123]
	v_mfma_f32_16x16x32_bf16 v[108:111], v[148:151], v[188:191], v[108:111]
	v_mfma_f32_16x16x32_bf16 v[104:107], v[156:159], v[188:191], v[104:107]
	v_mfma_f32_16x16x32_bf16 v[92:95], v[148:151], v[198:201], v[92:95]
	v_mfma_f32_16x16x32_bf16 v[88:91], v[156:159], v[198:201], v[88:91]
	v_mfma_f32_16x16x32_bf16 v[76:79], v[148:151], v[206:209], v[76:79]
	v_mfma_f32_16x16x32_bf16 v[72:75], v[156:159], v[206:209], v[72:75]
	v_mfma_f32_16x16x32_bf16 v[124:127], v[152:155], v[184:187], v[124:127]
	v_mfma_f32_16x16x32_bf16 v[120:123], v[160:163], v[184:187], v[120:123]
	v_mfma_f32_16x16x32_bf16 v[108:111], v[152:155], v[194:197], v[108:111]
	v_mfma_f32_16x16x32_bf16 v[104:107], v[160:163], v[194:197], v[104:107]
	v_mfma_f32_16x16x32_bf16 v[92:95], v[152:155], v[202:205], v[92:95]
	v_mfma_f32_16x16x32_bf16 v[88:91], v[160:163], v[202:205], v[88:91]
	v_mfma_f32_16x16x32_bf16 v[76:79], v[152:155], v[212:215], v[76:79]
	v_mfma_f32_16x16x32_bf16 v[72:75], v[160:163], v[212:215], v[72:75]
	s_setprio 0
	s_setprio 1
	v_mfma_f32_16x16x32_bf16 v[116:119], v[164:167], v[180:183], v[116:119]
	v_mfma_f32_16x16x32_bf16 v[112:115], v[172:175], v[180:183], v[112:115]
	v_mfma_f32_16x16x32_bf16 v[100:103], v[164:167], v[188:191], v[100:103]
	v_mfma_f32_16x16x32_bf16 v[96:99], v[172:175], v[188:191], v[96:99]
	v_mfma_f32_16x16x32_bf16 v[84:87], v[164:167], v[198:201], v[84:87]
	v_mfma_f32_16x16x32_bf16 v[80:83], v[172:175], v[198:201], v[80:83]
	v_mfma_f32_16x16x32_bf16 v[68:71], v[164:167], v[206:209], v[68:71]
	v_mfma_f32_16x16x32_bf16 v[64:67], v[172:175], v[206:209], v[64:67]
	v_mfma_f32_16x16x32_bf16 v[116:119], v[168:171], v[184:187], v[116:119]
	v_mfma_f32_16x16x32_bf16 v[112:115], v[176:179], v[184:187], v[112:115]
	v_mfma_f32_16x16x32_bf16 v[100:103], v[168:171], v[194:197], v[100:103]
	v_mfma_f32_16x16x32_bf16 v[96:99], v[176:179], v[194:197], v[96:99]
	v_mfma_f32_16x16x32_bf16 v[84:87], v[168:171], v[202:205], v[84:87]
	v_mfma_f32_16x16x32_bf16 v[80:83], v[176:179], v[202:205], v[80:83]
	v_mfma_f32_16x16x32_bf16 v[68:71], v[168:171], v[212:215], v[68:71]
	v_mfma_f32_16x16x32_bf16 v[64:67], v[176:179], v[212:215], v[64:67]
	s_barrier
; #define STAGE_A(bufoff, gbase) STAGEX(bufoff, gbase, voffA)
; #define STAGE_B(bufoff, gbase) STAGEX(bufoff, gbase, voffB)
; #define LDA(dst, b, h) do { _Pragma("unroll") for (int m = 0; m < 4; ++m) _Pragma("unroll") for (int k = 0; k < 2; ++k) dst[m][k] = *(const __attribute__((address_space(3))) bf16x8*)(lds + SA(b, h) + aoff + m * 2048 + k * 1024); } while (0)
; #define LDB(dst, b, h) do { _Pragma("unroll") for (int n = 0; n < 2; ++n) _Pragma("unroll") for (int k = 0; k < 2; ++k) dst[n][k] = *(const __attribute__((address_space(3))) bf16x8*)(lds + SB_(b, h) + boff + n * 2048 + k * 1024); } while (0)
; #define MMA(ai, bj, At, Bt_) do { __builtin_amdgcn_s_setprio(1); _Pragma("unroll") for (int m = 0; m < 4; ++m) _Pragma("unroll") for (int n = 0; n < 2; ++n) _Pragma("unroll") for (int k = 0; k < 2; ++k) \
;       acc[ai][bj][m][n] = __builtin_amdgcn_mfma_f32_16x16x32_bf16(Bt_[n][k], At[m][k], acc[ai][bj][m][n], 0, 0, 0); \
;     __builtin_amdgcn_s_setprio(0); } while (0)
; #define WAIT_V(n) asm volatile("s_waitcnt vmcnt(" #n ")" ::: "memory")
; #define WAIT_L(n) asm volatile("s_waitcnt lgkmcnt(" #n ")" ::: "memory")
; #define BAR __builtin_amdgcn_s_barrier()
; #define SCHED __builtin_amdgcn_sched_barrier(0)
; template <int MODE>
; DEV void gemm_phase(const bf16_t* __restrict__ A, const bf16_t* __restrict__ Bt, int M, int N, int K, bf16_t* __restrict__ Out, int ldo,
;                     const float* __restrict__ rstd, const float* __restrict__ rope) {
;     ...
;       LDA(At, 0, 1); STAGE_B(SB_(0, 0), b2); STAGE_B(SB_(0, 1), b2 + hstep); STAGE_A(SA(0, 0), a2);
;       WAIT_V(8); WAIT_L(0); BAR; MMA(1, 0, At, B0); MMA(1, 1, At, B1); BAR; SCHED;
;       LDB(B0, 1, 0); LDB(B1, 1, 1); SCHED; LDA(At, 1, 0); STAGE_A(SA(0, 1), a2 + hstep);
;       WAIT_V(8); WAIT_L(0); BAR; MMA(0, 0, At, B0); MMA(0, 1, At, B1); BAR; SCHED;
;       LDA(At, 1, 1); STAGE_B(SB_(1, 0), b3); STAGE_B(SB_(1, 1), b3 + hstep); STAGE_A(SA(1, 0), a3);
;       WAIT_V(8); WAIT_L(0); BAR; MMA(1, 0, At, B0); MMA(1, 1, At, B1); BAR; SCHED;
;     }
;     if (wr == 0) BAR;
	s_setprio 0
	s_add_i32 s22, s43, s24
	v_lshl_add_u64 v[222:223], v[222:223], 0, s[46:47]
	s_mov_b32 m0, s22
	ds_read_b128 v[180:183], v146 offset:49152
	ds_read_b128 v[184:187], v146 offset:50176
	ds_read_b128 v[188:191], v146 offset:51200
	ds_read_b128 v[194:197], v146 offset:52224
	ds_read_b128 v[198:201], v146 offset:53248
	ds_read_b128 v[202:205], v146 offset:54272
	ds_read_b128 v[206:209], v146 offset:55296
	ds_read_b128 v[212:215], v146 offset:56320
	global_load_lds_dwordx4 v[222:223], off
	s_add_i32 m0, s22, 0x2000
	s_add_u32 s20, s20, 0x80080
	v_lshl_add_u64 v[222:223], v[224:225], 0, s[46:47]
	s_addc_u32 s21, s21, 0
	s_add_i32 s22, s44, s24
	global_load_lds_dwordx4 v[222:223], off
	v_lshl_add_u64 v[222:223], s[20:21], 0, v[192:193]
	s_mov_b32 m0, s22
	s_nop 0
	global_load_lds_dwordx4 v[222:223], off
	v_lshl_add_u64 v[222:223], s[20:21], 0, v[128:129]
	s_add_i32 m0, s22, 0x2000
	s_nop 0
	global_load_lds_dwordx4 v[222:223], off
	v_lshl_add_u64 v[222:223], v[226:227], 0, s[46:47]
	s_mov_b32 m0, s29
	s_nop 0
	global_load_lds_dwordx4 v[222:223], off
	v_lshl_add_u64 v[222:223], v[228:229], 0, s[46:47]
	s_mov_b32 m0, s30
	s_nop 0
	global_load_lds_dwordx4 v[222:223], off
	s_waitcnt vmcnt(8)
	s_waitcnt lgkmcnt(0)
	s_setprio 1
	s_barrier
	v_mfma_f32_16x16x32_bf16 v[60:63], v[148:151], v[180:183], v[60:63]
	v_mfma_f32_16x16x32_bf16 v[56:59], v[156:159], v[180:183], v[56:59]
	v_mfma_f32_16x16x32_bf16 v[44:47], v[148:151], v[188:191], v[44:47]
	v_mfma_f32_16x16x32_bf16 v[40:43], v[156:159], v[188:191], v[40:43]
	v_mfma_f32_16x16x32_bf16 v[28:31], v[148:151], v[198:201], v[28:31]
	v_mfma_f32_16x16x32_bf16 v[24:27], v[156:159], v[198:201], v[24:27]
	v_mfma_f32_16x16x32_bf16 v[12:15], v[148:151], v[206:209], v[12:15]
	v_mfma_f32_16x16x32_bf16 v[4:7], v[156:159], v[206:209], v[4:7]
	v_mfma_f32_16x16x32_bf16 v[60:63], v[152:155], v[184:187], v[60:63]
	v_mfma_f32_16x16x32_bf16 v[56:59], v[160:163], v[184:187], v[56:59]
	v_mfma_f32_16x16x32_bf16 v[44:47], v[152:155], v[194:197], v[44:47]
	v_mfma_f32_16x16x32_bf16 v[40:43], v[160:163], v[194:197], v[40:43]
	v_mfma_f32_16x16x32_bf16 v[28:31], v[152:155], v[202:205], v[28:31]
	v_mfma_f32_16x16x32_bf16 v[24:27], v[160:163], v[202:205], v[24:27]
	v_mfma_f32_16x16x32_bf16 v[12:15], v[152:155], v[212:215], v[12:15]
	v_mfma_f32_16x16x32_bf16 v[4:7], v[160:163], v[212:215], v[4:7]
	s_setprio 0
	s_setprio 1
	v_mfma_f32_16x16x32_bf16 v[52:55], v[164:167], v[180:183], v[52:55]
	v_mfma_f32_16x16x32_bf16 v[48:51], v[172:175], v[180:183], v[48:51]
	v_mfma_f32_16x16x32_bf16 v[36:39], v[164:167], v[188:191], v[36:39]
	v_mfma_f32_16x16x32_bf16 v[32:35], v[172:175], v[188:191], v[32:35]
	v_mfma_f32_16x16x32_bf16 v[20:23], v[164:167], v[198:201], v[20:23]
	v_mfma_f32_16x16x32_bf16 v[16:19], v[172:175], v[198:201], v[16:19]
	v_mfma_f32_16x16x32_bf16 v[8:11], v[164:167], v[206:209], v[8:11]
	v_mfma_f32_16x16x32_bf16 v[0:3], v[172:175], v[206:209], v[0:3]
	v_mfma_f32_16x16x32_bf16 v[52:55], v[168:171], v[184:187], v[52:55]
	v_mfma_f32_16x16x32_bf16 v[48:51], v[176:179], v[184:187], v[48:51]
	v_mfma_f32_16x16x32_bf16 v[36:39], v[168:171], v[194:197], v[36:39]
	v_mfma_f32_16x16x32_bf16 v[32:35], v[176:179], v[194:197], v[32:35]
	v_mfma_f32_16x16x32_bf16 v[20:23], v[168:171], v[202:205], v[20:23]
	v_mfma_f32_16x16x32_bf16 v[16:19], v[176:179], v[202:205], v[16:19]
	v_mfma_f32_16x16x32_bf16 v[8:11], v[168:171], v[212:215], v[8:11]
	v_mfma_f32_16x16x32_bf16 v[0:3], v[176:179], v[212:215], v[0:3]
	s_barrier
	s_setprio 0
	s_add_i32 s42, s42, 2
	s_add_u32 s18, s18, 0x100
	s_addc_u32 s19, s19, 0
	s_cmp_gt_u32 s42, 29
	s_cbranch_scc0 .LBB0_618
	s_and_b64 vcc, exec, s[6:7]
	s_cbranch_vccz .LBB0_621
	s_barrier

; #define STAGE_A(bufoff, gbase) STAGEX(bufoff, gbase, voffA)
; #define STAGE_B(bufoff, gbase) STAGEX(bufoff, gbase, voffB)
; #define LDA(dst, b, h) do { _Pragma("unroll") for (int m = 0; m < 4; ++m) _Pragma("unroll") for (int k = 0; k < 2; ++k) dst[m][k] = *(const __attribute__((address_space(3))) bf16x8*)(lds + SA(b, h) + aoff + m * 2048 + k * 1024); } while (0)
; #define LDB(dst, b, h) do { _Pragma("unroll") for (int n = 0; n < 2; ++n) _Pragma("unroll") for (int k = 0; k < 2; ++k) dst[n][k] = *(const __attribute__((address_space(3))) bf16x8*)(lds + SB_(b, h) + boff + n * 2048 + k * 1024); } while (0)
; #define MMA(ai, bj, At, Bt_) do { __builtin_amdgcn_s_setprio(1); _Pragma("unroll") for (int m = 0; m < 4; ++m) _Pragma("unroll") for (int n = 0; n < 2; ++n) _Pragma("unroll") for (int k = 0; k < 2; ++k) \
;       acc[ai][bj][m][n] = __builtin_amdgcn_mfma_f32_16x16x32_bf16(Bt_[n][k], At[m][k], acc[ai][bj][m][n], 0, 0, 0); \
;     __builtin_amdgcn_s_setprio(0); } while (0)
; #define WAIT_V(n) asm volatile("s_waitcnt vmcnt(" #n ")" ::: "memory")
; #define WAIT_L(n) asm volatile("s_waitcnt lgkmcnt(" #n ")" ::: "memory")
; #define BAR __builtin_amdgcn_s_barrier()
; #define SCHED __builtin_amdgcn_sched_barrier(0)
; template <int MODE>
; DEV void gemm_phase(const bf16_t* __restrict__ A, const bf16_t* __restrict__ Bt, int M, int N, int K, bf16_t* __restrict__ Out, int ldo,
;                     const float* __restrict__ rstd, const float* __restrict__ rope) {
;     ...
;     for (int t = 0; t < nt; t += 2) {
;       const bool last = (t == nt - 2);
;       const char* a1 = cA + (size_t)(t + 1) * 128;
;       const char* a2 = last ? nA : cA + (size_t)(t + 2) * 128; const char* b2 = last ? nB : cB + (size_t)(t + 2) * 128;
;       const char* a3 = a2 + 128; const char* b3 = b2 + 128;
;       LDB(B0, 0, 0); LDB(B1, 0, 1); SCHED; LDA(At, 0, 0); STAGE_A(SA(1, 1), a1 + hstep);
;       WAIT_V(8); WAIT_L(0); BAR; MMA(0, 0, At, B0); MMA(0, 1, At, B1); BAR; SCHED;
;       LDA(At, 0, 1); STAGE_B(SB_(0, 0), b2); STAGE_B(SB_(0, 1), b2 + hstep); STAGE_A(SA(0, 0), a2);
;       WAIT_V(8); WAIT_L(0); BAR; MMA(1, 0, At, B0); MMA(1, 1, At, B1); BAR; SCHED;
.LBB0_690:
	s_add_u32 s14, s12, 0x100
	s_addc_u32 s15, s13, 0
	s_add_i32 s39, 0, 0x10000
	s_cmpk_eq_i32 s38, 0x54
	s_cselect_b32 s19, s9, s15
	s_cselect_b32 s18, s8, s14
	v_add_u32_e32 v143, s39, v141
	s_cselect_b32 s17, s35, s37
	s_cselect_b32 s16, s34, s36
	s_add_i32 s40, 0, 0x14000
	ds_read_b128 v[144:147], v143
	ds_read_b128 v[148:151], v143 offset:1024
	ds_read_b128 v[152:155], v143 offset:2048
	ds_read_b128 v[156:159], v143 offset:3072
	v_add_u32_e32 v143, s40, v141
	ds_read_b128 v[160:163], v143
	ds_read_b128 v[164:167], v143 offset:1024
	ds_read_b128 v[168:171], v143 offset:2048
	ds_read_b128 v[172:175], v143 offset:3072
	v_lshl_add_u64 v[212:213], s[12:13], 0, v[136:137]
	s_add_i32 m0, s21, 0xc000
	ds_read_b128 v[176:179], v142
	ds_read_b128 v[180:183], v142 offset:1024
	ds_read_b128 v[184:187], v142 offset:2048
	ds_read_b128 v[188:191], v142 offset:3072
	ds_read_b128 v[194:197], v142 offset:4096
	ds_read_b128 v[198:201], v142 offset:5120
	ds_read_b128 v[202:205], v142 offset:6144
	ds_read_b128 v[206:209], v142 offset:7168
	global_load_lds_dwordx4 v[212:213], off
	v_lshl_add_u64 v[212:213], s[12:13], 0, v[138:139]
	s_add_i32 m0, s21, 0xe000
	s_nop 0
	global_load_lds_dwordx4 v[212:213], off
	s_waitcnt vmcnt(8)
	s_waitcnt lgkmcnt(0)
	s_setprio 1
	s_barrier
	v_mfma_f32_16x16x32_bf16 v[124:127], v[144:147], v[176:179], v[124:127]
	v_mfma_f32_16x16x32_bf16 v[120:123], v[152:155], v[176:179], v[120:123]
	v_mfma_f32_16x16x32_bf16 v[116:119], v[144:147], v[184:187], v[116:119]
	v_mfma_f32_16x16x32_bf16 v[112:115], v[152:155], v[184:187], v[112:115]
	v_mfma_f32_16x16x32_bf16 v[100:103], v[144:147], v[194:197], v[100:103]
	v_mfma_f32_16x16x32_bf16 v[96:99], v[152:155], v[194:197], v[96:99]
	v_mfma_f32_16x16x32_bf16 v[84:87], v[144:147], v[202:205], v[84:87]
	v_mfma_f32_16x16x32_bf16 v[80:83], v[152:155], v[202:205], v[80:83]
	v_mfma_f32_16x16x32_bf16 v[124:127], v[148:151], v[180:183], v[124:127]
	v_mfma_f32_16x16x32_bf16 v[120:123], v[156:159], v[180:183], v[120:123]
	v_mfma_f32_16x16x32_bf16 v[116:119], v[148:151], v[188:191], v[116:119]
	v_mfma_f32_16x16x32_bf16 v[112:115], v[156:159], v[188:191], v[112:115]
	v_mfma_f32_16x16x32_bf16 v[100:103], v[148:151], v[198:201], v[100:103]
	v_mfma_f32_16x16x32_bf16 v[96:99], v[156:159], v[198:201], v[96:99]
	v_mfma_f32_16x16x32_bf16 v[84:87], v[148:151], v[206:209], v[84:87]
	v_mfma_f32_16x16x32_bf16 v[80:83], v[156:159], v[206:209], v[80:83]
	s_setprio 0
	s_setprio 1
	v_mfma_f32_16x16x32_bf16 v[108:111], v[160:163], v[176:179], v[108:111]
	v_mfma_f32_16x16x32_bf16 v[104:107], v[168:171], v[176:179], v[104:107]
	v_mfma_f32_16x16x32_bf16 v[92:95], v[160:163], v[184:187], v[92:95]
	v_mfma_f32_16x16x32_bf16 v[88:91], v[168:171], v[184:187], v[88:91]
	v_mfma_f32_16x16x32_bf16 v[76:79], v[160:163], v[194:197], v[76:79]
	v_mfma_f32_16x16x32_bf16 v[72:75], v[168:171], v[194:197], v[72:75]
	v_mfma_f32_16x16x32_bf16 v[68:71], v[160:163], v[202:205], v[68:71]
	v_mfma_f32_16x16x32_bf16 v[64:67], v[168:171], v[202:205], v[64:67]
	v_mfma_f32_16x16x32_bf16 v[108:111], v[164:167], v[180:183], v[108:111]
	v_mfma_f32_16x16x32_bf16 v[104:107], v[172:175], v[180:183], v[104:107]
	v_mfma_f32_16x16x32_bf16 v[92:95], v[164:167], v[188:191], v[92:95]
	v_mfma_f32_16x16x32_bf16 v[88:91], v[172:175], v[188:191], v[88:91]
	v_mfma_f32_16x16x32_bf16 v[76:79], v[164:167], v[198:201], v[76:79]
	v_mfma_f32_16x16x32_bf16 v[72:75], v[172:175], v[198:201], v[72:75]
	v_mfma_f32_16x16x32_bf16 v[68:71], v[164:167], v[206:209], v[68:71]
	v_mfma_f32_16x16x32_bf16 v[64:67], v[172:175], v[206:209], v[64:67]
	s_barrier
	s_setprio 0
	s_add_i32 s12, s39, s20
	v_lshl_add_u64 v[212:213], s[16:17], 0, v[192:193]
	s_mov_b32 m0, s12
	ds_read_b128 v[176:179], v142 offset:16384
	ds_read_b128 v[180:183], v142 offset:17408
	ds_read_b128 v[184:187], v142 offset:18432
	ds_read_b128 v[188:191], v142 offset:19456
	ds_read_b128 v[194:197], v142 offset:20480
	ds_read_b128 v[198:201], v142 offset:21504
	ds_read_b128 v[202:205], v142 offset:22528
	ds_read_b128 v[206:209], v142 offset:23552
	global_load_lds_dwordx4 v[212:213], off
	s_add_i32 m0, s12, 0x2000
	s_add_u32 s12, s16, 0x160000
	v_lshl_add_u64 v[214:215], s[16:17], 0, v[128:129]
	s_addc_u32 s13, s17, 0
	s_add_i32 s39, s40, s20
	global_load_lds_dwordx4 v[214:215], off
	v_lshl_add_u64 v[222:223], s[12:13], 0, v[192:193]
	s_mov_b32 m0, s39
	v_lshl_add_u64 v[224:225], s[18:19], 0, v[130:131]
	global_load_lds_dwordx4 v[222:223], off
	v_lshl_add_u64 v[222:223], s[12:13], 0, v[128:129]
	s_add_i32 m0, s39, 0x2000
	s_nop 0
	global_load_lds_dwordx4 v[222:223], off
	v_lshl_add_u64 v[222:223], s[18:19], 0, v[132:133]
	s_mov_b32 m0, s21
	s_nop 0
	global_load_lds_dwordx4 v[222:223], off
	s_mov_b32 m0, s22
	s_nop 0
	global_load_lds_dwordx4 v[224:225], off
	s_waitcnt vmcnt(8)
	s_waitcnt lgkmcnt(0)
	s_setprio 1
	s_barrier
; #define STAGE_A(bufoff, gbase) STAGEX(bufoff, gbase, voffA)
; #define STAGE_B(bufoff, gbase) STAGEX(bufoff, gbase, voffB)
; #define LDA(dst, b, h) do { _Pragma("unroll") for (int m = 0; m < 4; ++m) _Pragma("unroll") for (int k = 0; k < 2; ++k) dst[m][k] = *(const __attribute__((address_space(3))) bf16x8*)(lds + SA(b, h) + aoff + m * 2048 + k * 1024); } while (0)
; #define LDB(dst, b, h) do { _Pragma("unroll") for (int n = 0; n < 2; ++n) _Pragma("unroll") for (int k = 0; k < 2; ++k) dst[n][k] = *(const __attribute__((address_space(3))) bf16x8*)(lds + SB_(b, h) + boff + n * 2048 + k * 1024); } while (0)
; #define MMA(ai, bj, At, Bt_) do { __builtin_amdgcn_s_setprio(1); _Pragma("unroll") for (int m = 0; m < 4; ++m) _Pragma("unroll") for (int n = 0; n < 2; ++n) _Pragma("unroll") for (int k = 0; k < 2; ++k) \
;       acc[ai][bj][m][n] = __builtin_amdgcn_mfma_f32_16x16x32_bf16(Bt_[n][k], At[m][k], acc[ai][bj][m][n], 0, 0, 0); \
;     __builtin_amdgcn_s_setprio(0); } while (0)
; #define WAIT_V(n) asm volatile("s_waitcnt vmcnt(" #n ")" ::: "memory")
; #define WAIT_L(n) asm volatile("s_waitcnt lgkmcnt(" #n ")" ::: "memory")
; #define BAR __builtin_amdgcn_s_barrier()
; #define SCHED __builtin_amdgcn_sched_barrier(0)
; template <int MODE>
; DEV void gemm_phase(const bf16_t* __restrict__ A, const bf16_t* __restrict__ Bt, int M, int N, int K, bf16_t* __restrict__ Out, int ldo,
;                     const float* __restrict__ rstd, const float* __restrict__ rope) {
;     ...
;       LDB(B0, 0, 0); LDB(B1, 0, 1); SCHED; LDA(At, 0, 0); STAGE_A(SA(1, 1), a1 + hstep);
;       WAIT_V(8); WAIT_L(0); BAR; MMA(0, 0, At, B0); MMA(0, 1, At, B1); BAR; SCHED;
;       LDA(At, 0, 1); STAGE_B(SB_(0, 0), b2); STAGE_B(SB_(0, 1), b2 + hstep); STAGE_A(SA(0, 0), a2);
;       WAIT_V(8); WAIT_L(0); BAR; MMA(1, 0, At, B0); MMA(1, 1, At, B1); BAR; SCHED;
;       LDB(B0, 1, 0); LDB(B1, 1, 1); SCHED; LDA(At, 1, 0); STAGE_A(SA(0, 1), a2 + hstep);
;       WAIT_V(8); WAIT_L(0); BAR; MMA(0, 0, At, B0); MMA(0, 1, At, B1); BAR; SCHED;
;       LDA(At, 1, 1); STAGE_B(SB_(1, 0), b3); STAGE_B(SB_(1, 1), b3 + hstep); STAGE_A(SA(1, 0), a3);
;       WAIT_V(8); WAIT_L(0); BAR; MMA(1, 0, At, B0); MMA(1, 1, At, B1); BAR; SCHED;
	v_mfma_f32_16x16x32_bf16 v[60:63], v[144:147], v[176:179], v[60:63]
	v_mfma_f32_16x16x32_bf16 v[56:59], v[152:155], v[176:179], v[56:59]
	v_mfma_f32_16x16x32_bf16 v[52:55], v[144:147], v[184:187], v[52:55]
	v_mfma_f32_16x16x32_bf16 v[48:51], v[152:155], v[184:187], v[48:51]
	v_mfma_f32_16x16x32_bf16 v[36:39], v[144:147], v[194:197], v[36:39]
	v_mfma_f32_16x16x32_bf16 v[32:35], v[152:155], v[194:197], v[32:35]
	v_mfma_f32_16x16x32_bf16 v[20:23], v[144:147], v[202:205], v[20:23]
	v_mfma_f32_16x16x32_bf16 v[16:19], v[152:155], v[202:205], v[16:19]
	v_mfma_f32_16x16x32_bf16 v[60:63], v[148:151], v[180:183], v[60:63]
	v_mfma_f32_16x16x32_bf16 v[56:59], v[156:159], v[180:183], v[56:59]
	v_mfma_f32_16x16x32_bf16 v[52:55], v[148:151], v[188:191], v[52:55]
	v_mfma_f32_16x16x32_bf16 v[48:51], v[156:159], v[188:191], v[48:51]
	v_mfma_f32_16x16x32_bf16 v[36:39], v[148:151], v[198:201], v[36:39]
	v_mfma_f32_16x16x32_bf16 v[32:35], v[156:159], v[198:201], v[32:35]
	v_mfma_f32_16x16x32_bf16 v[20:23], v[148:151], v[206:209], v[20:23]
	v_mfma_f32_16x16x32_bf16 v[16:19], v[156:159], v[206:209], v[16:19]
	s_setprio 0
	s_setprio 1
	v_mfma_f32_16x16x32_bf16 v[44:47], v[160:163], v[176:179], v[44:47]
	v_mfma_f32_16x16x32_bf16 v[40:43], v[168:171], v[176:179], v[40:43]
	v_mfma_f32_16x16x32_bf16 v[28:31], v[160:163], v[184:187], v[28:31]
	v_mfma_f32_16x16x32_bf16 v[24:27], v[168:171], v[184:187], v[24:27]
	v_mfma_f32_16x16x32_bf16 v[12:15], v[160:163], v[194:197], v[12:15]
	v_mfma_f32_16x16x32_bf16 v[8:11], v[168:171], v[194:197], v[8:11]
	v_mfma_f32_16x16x32_bf16 v[4:7], v[160:163], v[202:205], v[4:7]
	v_mfma_f32_16x16x32_bf16 v[0:3], v[168:171], v[202:205], v[0:3]
	v_mfma_f32_16x16x32_bf16 v[44:47], v[164:167], v[180:183], v[44:47]
	v_mfma_f32_16x16x32_bf16 v[40:43], v[172:175], v[180:183], v[40:43]
	v_mfma_f32_16x16x32_bf16 v[28:31], v[164:167], v[188:191], v[28:31]
	v_mfma_f32_16x16x32_bf16 v[24:27], v[172:175], v[188:191], v[24:27]
	v_mfma_f32_16x16x32_bf16 v[12:15], v[164:167], v[198:201], v[12:15]
	v_mfma_f32_16x16x32_bf16 v[8:11], v[172:175], v[198:201], v[8:11]
	v_mfma_f32_16x16x32_bf16 v[4:7], v[164:167], v[206:209], v[4:7]
	v_mfma_f32_16x16x32_bf16 v[0:3], v[172:175], v[206:209], v[0:3]
	s_barrier
	s_setprio 0
	s_add_i32 s39, 0, 0x18000
	v_add_u32_e32 v143, s39, v141
	s_add_i32 s40, 0, 0x1c000
	ds_read_b128 v[144:147], v143
	ds_read_b128 v[148:151], v143 offset:1024
	ds_read_b128 v[152:155], v143 offset:2048
	ds_read_b128 v[156:159], v143 offset:3072
	v_add_u32_e32 v143, s40, v141
	ds_read_b128 v[160:163], v143
	ds_read_b128 v[164:167], v143 offset:1024
	ds_read_b128 v[168:171], v143 offset:2048
	ds_read_b128 v[172:175], v143 offset:3072
	s_add_u32 s12, s18, 0x160000
	s_addc_u32 s13, s19, 0
	s_mov_b32 m0, s23
	v_lshl_add_u64 v[226:227], s[12:13], 0, v[132:133]
	ds_read_b128 v[176:179], v142 offset:32768
	ds_read_b128 v[180:183], v142 offset:33792
	ds_read_b128 v[184:187], v142 offset:34816
	ds_read_b128 v[188:191], v142 offset:35840
	ds_read_b128 v[194:197], v142 offset:36864
	ds_read_b128 v[198:201], v142 offset:37888
	ds_read_b128 v[202:205], v142 offset:38912
	ds_read_b128 v[206:209], v142 offset:39936
	global_load_lds_dwordx4 v[226:227], off
	v_lshl_add_u64 v[226:227], s[12:13], 0, v[130:131]
	s_mov_b32 m0, s24
	s_nop 0
	global_load_lds_dwordx4 v[226:227], off
	s_waitcnt vmcnt(8)
	s_waitcnt lgkmcnt(0)
	s_setprio 1
	s_barrier
	v_mfma_f32_16x16x32_bf16 v[124:127], v[144:147], v[176:179], v[124:127]
	v_mfma_f32_16x16x32_bf16 v[120:123], v[152:155], v[176:179], v[120:123]
	v_mfma_f32_16x16x32_bf16 v[116:119], v[144:147], v[184:187], v[116:119]
	v_mfma_f32_16x16x32_bf16 v[112:115], v[152:155], v[184:187], v[112:115]
	v_mfma_f32_16x16x32_bf16 v[100:103], v[144:147], v[194:197], v[100:103]
	v_mfma_f32_16x16x32_bf16 v[96:99], v[152:155], v[194:197], v[96:99]
	v_mfma_f32_16x16x32_bf16 v[84:87], v[144:147], v[202:205], v[84:87]
	v_mfma_f32_16x16x32_bf16 v[80:83], v[152:155], v[202:205], v[80:83]
	v_mfma_f32_16x16x32_bf16 v[124:127], v[148:151], v[180:183], v[124:127]
	v_mfma_f32_16x16x32_bf16 v[120:123], v[156:159], v[180:183], v[120:123]
	v_mfma_f32_16x16x32_bf16 v[116:119], v[148:151], v[188:191], v[116:119]
	v_mfma_f32_16x16x32_bf16 v[112:115], v[156:159], v[188:191], v[112:115]
	v_mfma_f32_16x16x32_bf16 v[100:103], v[148:151], v[198:201], v[100:103]
	v_mfma_f32_16x16x32_bf16 v[96:99], v[156:159], v[198:201], v[96:99]
	v_mfma_f32_16x16x32_bf16 v[84:87], v[148:151], v[206:209], v[84:87]
	v_mfma_f32_16x16x32_bf16 v[80:83], v[156:159], v[206:209], v[80:83]
	s_setprio 0
	s_setprio 1
	v_mfma_f32_16x16x32_bf16 v[108:111], v[160:163], v[176:179], v[108:111]
	v_mfma_f32_16x16x32_bf16 v[104:107], v[168:171], v[176:179], v[104:107]
	v_mfma_f32_16x16x32_bf16 v[92:95], v[160:163], v[184:187], v[92:95]
	v_mfma_f32_16x16x32_bf16 v[88:91], v[168:171], v[184:187], v[88:91]
	v_mfma_f32_16x16x32_bf16 v[76:79], v[160:163], v[194:197], v[76:79]
	v_mfma_f32_16x16x32_bf16 v[72:75], v[168:171], v[194:197], v[72:75]
	v_mfma_f32_16x16x32_bf16 v[68:71], v[160:163], v[202:205], v[68:71]
	v_mfma_f32_16x16x32_bf16 v[64:67], v[168:171], v[202:205], v[64:67]
	v_mfma_f32_16x16x32_bf16 v[108:111], v[164:167], v[180:183], v[108:111]
	v_mfma_f32_16x16x32_bf16 v[104:107], v[172:175], v[180:183], v[104:107]
	v_mfma_f32_16x16x32_bf16 v[92:95], v[164:167], v[188:191], v[92:95]
	v_mfma_f32_16x16x32_bf16 v[88:91], v[172:175], v[188:191], v[88:91]
	v_mfma_f32_16x16x32_bf16 v[76:79], v[164:167], v[198:201], v[76:79]
	v_mfma_f32_16x16x32_bf16 v[72:75], v[172:175], v[198:201], v[72:75]
	v_mfma_f32_16x16x32_bf16 v[68:71], v[164:167], v[206:209], v[68:71]
	v_mfma_f32_16x16x32_bf16 v[64:67], v[172:175], v[206:209], v[64:67]
	s_barrier
; #define STAGE_A(bufoff, gbase) STAGEX(bufoff, gbase, voffA)
; #define STAGE_B(bufoff, gbase) STAGEX(bufoff, gbase, voffB)
; #define LDA(dst, b, h) do { _Pragma("unroll") for (int m = 0; m < 4; ++m) _Pragma("unroll") for (int k = 0; k < 2; ++k) dst[m][k] = *(const __attribute__((address_space(3))) bf16x8*)(lds + SA(b, h) + aoff + m * 2048 + k * 1024); } while (0)
; #define LDB(dst, b, h) do { _Pragma("unroll") for (int n = 0; n < 2; ++n) _Pragma("unroll") for (int k = 0; k < 2; ++k) dst[n][k] = *(const __attribute__((address_space(3))) bf16x8*)(lds + SB_(b, h) + boff + n * 2048 + k * 1024); } while (0)
; #define MMA(ai, bj, At, Bt_) do { __builtin_amdgcn_s_setprio(1); _Pragma("unroll") for (int m = 0; m < 4; ++m) _Pragma("unroll") for (int n = 0; n < 2; ++n) _Pragma("unroll") for (int k = 0; k < 2; ++k) \
;       acc[ai][bj][m][n] = __builtin_amdgcn_mfma_f32_16x16x32_bf16(Bt_[n][k], At[m][k], acc[ai][bj][m][n], 0, 0, 0); \
;     __builtin_amdgcn_s_setprio(0); } while (0)
; #define WAIT_V(n) asm volatile("s_waitcnt vmcnt(" #n ")" ::: "memory")
; #define WAIT_L(n) asm volatile("s_waitcnt lgkmcnt(" #n ")" ::: "memory")
; #define BAR __builtin_amdgcn_s_barrier()
; #define SCHED __builtin_amdgcn_sched_barrier(0)
; template <int MODE>
; DEV void gemm_phase(const bf16_t* __restrict__ A, const bf16_t* __restrict__ Bt, int M, int N, int K, bf16_t* __restrict__ Out, int ldo,
;                     const float* __restrict__ rstd, const float* __restrict__ rope) {
;     ...
;       LDA(At, 0, 1); STAGE_B(SB_(0, 0), b2); STAGE_B(SB_(0, 1), b2 + hstep); STAGE_A(SA(0, 0), a2);
;       WAIT_V(8); WAIT_L(0); BAR; MMA(1, 0, At, B0); MMA(1, 1, At, B1); BAR; SCHED;
;       LDB(B0, 1, 0); LDB(B1, 1, 1); SCHED; LDA(At, 1, 0); STAGE_A(SA(0, 1), a2 + hstep);
;       WAIT_V(8); WAIT_L(0); BAR; MMA(0, 0, At, B0); MMA(0, 1, At, B1); BAR; SCHED;
;       LDA(At, 1, 1); STAGE_B(SB_(1, 0), b3); STAGE_B(SB_(1, 1), b3 + hstep); STAGE_A(SA(1, 0), a3);
;       WAIT_V(8); WAIT_L(0); BAR; MMA(1, 0, At, B0); MMA(1, 1, At, B1); BAR; SCHED;
;     }
;     if (wr == 0) BAR;
	s_setprio 0
	s_add_i32 s12, s39, s20
	v_lshl_add_u64 v[212:213], v[212:213], 0, s[42:43]
	s_mov_b32 m0, s12
	ds_read_b128 v[176:179], v142 offset:49152
	ds_read_b128 v[180:183], v142 offset:50176
	ds_read_b128 v[184:187], v142 offset:51200
	ds_read_b128 v[188:191], v142 offset:52224
	ds_read_b128 v[194:197], v142 offset:53248
	ds_read_b128 v[198:201], v142 offset:54272
	ds_read_b128 v[202:205], v142 offset:55296
	ds_read_b128 v[206:209], v142 offset:56320
	global_load_lds_dwordx4 v[212:213], off
	s_add_i32 m0, s12, 0x2000
	s_add_u32 s12, s16, 0x160080
	v_lshl_add_u64 v[212:213], v[214:215], 0, s[42:43]
	s_addc_u32 s13, s17, 0
	s_add_i32 s16, s40, s20
	global_load_lds_dwordx4 v[212:213], off
	v_lshl_add_u64 v[212:213], s[12:13], 0, v[192:193]
	s_mov_b32 m0, s16
	s_nop 0
	global_load_lds_dwordx4 v[212:213], off
	v_lshl_add_u64 v[212:213], s[12:13], 0, v[128:129]
	s_add_i32 m0, s16, 0x2000
	s_nop 0
	global_load_lds_dwordx4 v[212:213], off
	v_lshl_add_u64 v[212:213], v[222:223], 0, s[42:43]
	s_mov_b32 m0, s25
	s_nop 0
	global_load_lds_dwordx4 v[212:213], off
	v_lshl_add_u64 v[212:213], v[224:225], 0, s[42:43]
	s_mov_b32 m0, s26
	s_nop 0
	global_load_lds_dwordx4 v[212:213], off
	s_waitcnt vmcnt(8)
	s_waitcnt lgkmcnt(0)
	s_setprio 1
	s_barrier
	v_mfma_f32_16x16x32_bf16 v[60:63], v[144:147], v[176:179], v[60:63]
	v_mfma_f32_16x16x32_bf16 v[56:59], v[152:155], v[176:179], v[56:59]
	v_mfma_f32_16x16x32_bf16 v[52:55], v[144:147], v[184:187], v[52:55]
	v_mfma_f32_16x16x32_bf16 v[48:51], v[152:155], v[184:187], v[48:51]
	v_mfma_f32_16x16x32_bf16 v[36:39], v[144:147], v[194:197], v[36:39]
	v_mfma_f32_16x16x32_bf16 v[32:35], v[152:155], v[194:197], v[32:35]
	v_mfma_f32_16x16x32_bf16 v[20:23], v[144:147], v[202:205], v[20:23]
	v_mfma_f32_16x16x32_bf16 v[16:19], v[152:155], v[202:205], v[16:19]
	v_mfma_f32_16x16x32_bf16 v[60:63], v[148:151], v[180:183], v[60:63]
	v_mfma_f32_16x16x32_bf16 v[56:59], v[156:159], v[180:183], v[56:59]
	v_mfma_f32_16x16x32_bf16 v[52:55], v[148:151], v[188:191], v[52:55]
	v_mfma_f32_16x16x32_bf16 v[48:51], v[156:159], v[188:191], v[48:51]
	v_mfma_f32_16x16x32_bf16 v[36:39], v[148:151], v[198:201], v[36:39]
	v_mfma_f32_16x16x32_bf16 v[32:35], v[156:159], v[198:201], v[32:35]
	v_mfma_f32_16x16x32_bf16 v[20:23], v[148:151], v[206:209], v[20:23]
	v_mfma_f32_16x16x32_bf16 v[16:19], v[156:159], v[206:209], v[16:19]
	s_setprio 0
	s_setprio 1
	v_mfma_f32_16x16x32_bf16 v[44:47], v[160:163], v[176:179], v[44:47]
	v_mfma_f32_16x16x32_bf16 v[40:43], v[168:171], v[176:179], v[40:43]
	v_mfma_f32_16x16x32_bf16 v[28:31], v[160:163], v[184:187], v[28:31]
	v_mfma_f32_16x16x32_bf16 v[24:27], v[168:171], v[184:187], v[24:27]
	v_mfma_f32_16x16x32_bf16 v[12:15], v[160:163], v[194:197], v[12:15]
	v_mfma_f32_16x16x32_bf16 v[8:11], v[168:171], v[194:197], v[8:11]
	v_mfma_f32_16x16x32_bf16 v[4:7], v[160:163], v[202:205], v[4:7]
	v_mfma_f32_16x16x32_bf16 v[0:3], v[168:171], v[202:205], v[0:3]
	v_mfma_f32_16x16x32_bf16 v[44:47], v[164:167], v[180:183], v[44:47]
	v_mfma_f32_16x16x32_bf16 v[40:43], v[172:175], v[180:183], v[40:43]
	v_mfma_f32_16x16x32_bf16 v[28:31], v[164:167], v[188:191], v[28:31]
	v_mfma_f32_16x16x32_bf16 v[24:27], v[172:175], v[188:191], v[24:27]
	v_mfma_f32_16x16x32_bf16 v[12:15], v[164:167], v[198:201], v[12:15]
	v_mfma_f32_16x16x32_bf16 v[8:11], v[172:175], v[198:201], v[8:11]
	v_mfma_f32_16x16x32_bf16 v[4:7], v[164:167], v[206:209], v[4:7]
	v_mfma_f32_16x16x32_bf16 v[0:3], v[172:175], v[206:209], v[0:3]
	s_barrier
	s_setprio 0
	s_add_i32 s38, s38, 2
	s_add_u32 s36, s36, 0x100
	s_addc_u32 s37, s37, 0
	s_cmpk_gt_u32 s38, 0x55
	s_mov_b64 s[12:13], s[14:15]
	s_cbranch_scc0 .LBB0_690
	s_and_b64 vcc, exec, s[4:5]
	s_cbranch_vccz .LBB0_693
	s_barrier
